# P1/P8 swiglu epilogue via LDS transpose + wide stores; GDN scan: hoisted gdn_norm loads, decay prefetched one chunk ahead, counted vmcnt
# baseline (speedup 1.0000x reference)
.LBB0_513:
	s_waitcnt vmcnt(0)
	v_and_b32_e32 v198, 31, v208
	v_bfe_u32 v199, v208, 5, 1
	v_lshrrev_b32_e32 v204, 6, v208
	v_lshrrev_b32_e32 v205, 8, v208
	v_lshlrev_b32_e32 v194, 9, v205
	v_lshl_add_u32 v194, v199, 4, v194
	v_add_u32_e32 v194, 0x24000, v194
	ds_read_b128 v[128:131], v194 offset:0
	ds_read_b128 v[132:135], v194 offset:32
	ds_read_b128 v[136:139], v194 offset:64
	ds_read_b128 v[140:143], v194 offset:96
	v_mul_u32_u24_e32 v195, 0x2100, v204
	v_mul_u32_u24_e32 v210, 0x108, v198
	v_add_u32_e32 v211, v195, v210
	v_lshl_add_u32 v211, v199, 3, v211
	v_bfe_u32 v212, v208, 4, 2
	v_bfe_u32 v213, v208, 2, 2
	v_lshl_add_u32 v213, v212, 3, v213
	v_mul_u32_u24_e32 v213, 0x108, v213
	v_and_b32_e32 v210, 3, v208
	v_lshl_add_u32 v213, v210, 3, v213
	v_add_u32_e32 v196, v195, v213
	v_mov_b32_e32 v195, v211
	s_mul_i32 s8, s6, 0x1600
	s_lshl_b32 s9, s27, 8
	s_add_i32 s8, s8, s9
	v_and_b32_e32 v210, 15, v208
	v_lshl_add_u32 v210, v205, 7, v210
	v_mul_u32_u24_e32 v210, 0x1600, v210
	v_and_b32_e32 v211, 3, v204
	v_lshlrev_b32_e32 v211, 6, v211
	v_lshl_add_u32 v211, v212, 4, v211
	v_add3_u32 v197, v210, v211, s8
	s_waitcnt lgkmcnt(3)
	ds_read_b128 v[144:147], v194 offset:128
	v_mul_f32_e32 v96, v96, v128
	v_mul_f32_e32 v97, v97, v129
	v_mul_f32_e32 v98, v98, v130
	v_mul_f32_e32 v99, v99, v131
	v_mul_f32_e32 v210, 0xbfb8aa3b, v96
	v_mul_f32_e32 v211, 0xbfb8aa3b, v97
	v_mul_f32_e32 v212, 0xbfb8aa3b, v98
	v_mul_f32_e32 v213, 0xbfb8aa3b, v99
	v_exp_f32_e32 v210, v210
	v_exp_f32_e32 v211, v211
	v_exp_f32_e32 v212, v212
	v_exp_f32_e32 v213, v213
	v_mul_f32_e32 v112, v112, v128
	v_mul_f32_e32 v113, v113, v129
	v_mul_f32_e32 v114, v114, v130
	v_mul_f32_e32 v115, v115, v131
	v_add_f32_e32 v210, 1.0, v210
	v_add_f32_e32 v211, 1.0, v211
	v_add_f32_e32 v212, 1.0, v212
	v_add_f32_e32 v213, 1.0, v213
	v_rcp_f32_e32 v210, v210
	v_rcp_f32_e32 v211, v211
	v_rcp_f32_e32 v212, v212
	v_rcp_f32_e32 v213, v213
	v_mul_f32_e32 v96, v96, v210
	v_mul_f32_e32 v97, v97, v211
	v_mul_f32_e32 v98, v98, v212
	v_mul_f32_e32 v99, v99, v213
	v_mul_f32_e32 v96, v112, v96
	v_mul_f32_e32 v97, v113, v97
	v_mul_f32_e32 v98, v114, v98
	v_mul_f32_e32 v99, v115, v99
	v_cvt_pk_bf16_f32 v214, v96, v97
	v_cvt_pk_bf16_f32 v215, v98, v99
	ds_write_b64 v195, v[214:215] offset:0
	s_waitcnt lgkmcnt(4)
	ds_read_b128 v[148:151], v194 offset:160
	v_mul_f32_e32 v100, v100, v132
	v_mul_f32_e32 v101, v101, v133
	v_mul_f32_e32 v102, v102, v134
	v_mul_f32_e32 v103, v103, v135
	v_mul_f32_e32 v210, 0xbfb8aa3b, v100
	v_mul_f32_e32 v211, 0xbfb8aa3b, v101
	v_mul_f32_e32 v212, 0xbfb8aa3b, v102
	v_mul_f32_e32 v213, 0xbfb8aa3b, v103
	v_exp_f32_e32 v210, v210
	v_exp_f32_e32 v211, v211
	v_exp_f32_e32 v212, v212
	v_exp_f32_e32 v213, v213
	v_mul_f32_e32 v116, v116, v132
	v_mul_f32_e32 v117, v117, v133
	v_mul_f32_e32 v118, v118, v134
	v_mul_f32_e32 v119, v119, v135
	v_add_f32_e32 v210, 1.0, v210
	v_add_f32_e32 v211, 1.0, v211
	v_add_f32_e32 v212, 1.0, v212
	v_add_f32_e32 v213, 1.0, v213
	v_rcp_f32_e32 v210, v210
	v_rcp_f32_e32 v211, v211
	v_rcp_f32_e32 v212, v212
	v_rcp_f32_e32 v213, v213
	v_mul_f32_e32 v100, v100, v210
	v_mul_f32_e32 v101, v101, v211
	v_mul_f32_e32 v102, v102, v212
	v_mul_f32_e32 v103, v103, v213
	v_mul_f32_e32 v100, v116, v100
	v_mul_f32_e32 v101, v117, v101
	v_mul_f32_e32 v102, v118, v102
	v_mul_f32_e32 v103, v119, v103
	v_cvt_pk_bf16_f32 v216, v100, v101
	v_cvt_pk_bf16_f32 v217, v102, v103
	ds_write_b64 v195, v[216:217] offset:16
	s_waitcnt lgkmcnt(5)
	ds_read_b128 v[152:155], v194 offset:192
	v_mul_f32_e32 v104, v104, v136
	v_mul_f32_e32 v105, v105, v137
	v_mul_f32_e32 v106, v106, v138
	v_mul_f32_e32 v107, v107, v139
	v_mul_f32_e32 v210, 0xbfb8aa3b, v104
	v_mul_f32_e32 v211, 0xbfb8aa3b, v105
	v_mul_f32_e32 v212, 0xbfb8aa3b, v106
	v_mul_f32_e32 v213, 0xbfb8aa3b, v107
	v_exp_f32_e32 v210, v210
	v_exp_f32_e32 v211, v211
	v_exp_f32_e32 v212, v212
	v_exp_f32_e32 v213, v213
	v_mul_f32_e32 v120, v120, v136
	v_mul_f32_e32 v121, v121, v137
	v_mul_f32_e32 v122, v122, v138
	v_mul_f32_e32 v123, v123, v139
	v_add_f32_e32 v210, 1.0, v210
	v_add_f32_e32 v211, 1.0, v211
	v_add_f32_e32 v212, 1.0, v212
	v_add_f32_e32 v213, 1.0, v213
	v_rcp_f32_e32 v210, v210
	v_rcp_f32_e32 v211, v211
	v_rcp_f32_e32 v212, v212
	v_rcp_f32_e32 v213, v213
	v_mul_f32_e32 v104, v104, v210
	v_mul_f32_e32 v105, v105, v211
	v_mul_f32_e32 v106, v106, v212
	v_mul_f32_e32 v107, v107, v213
	v_mul_f32_e32 v104, v120, v104
	v_mul_f32_e32 v105, v121, v105
	v_mul_f32_e32 v106, v122, v106
	v_mul_f32_e32 v107, v123, v107
	v_cvt_pk_bf16_f32 v218, v104, v105
	v_cvt_pk_bf16_f32 v219, v106, v107
	ds_write_b64 v195, v[218:219] offset:32
	s_waitcnt lgkmcnt(6)
	ds_read_b128 v[156:159], v194 offset:224
	v_mul_f32_e32 v108, v108, v140
	v_mul_f32_e32 v109, v109, v141
	v_mul_f32_e32 v110, v110, v142
	v_mul_f32_e32 v111, v111, v143
	v_mul_f32_e32 v210, 0xbfb8aa3b, v108
	v_mul_f32_e32 v211, 0xbfb8aa3b, v109
	v_mul_f32_e32 v212, 0xbfb8aa3b, v110
	v_mul_f32_e32 v213, 0xbfb8aa3b, v111
	v_exp_f32_e32 v210, v210
	v_exp_f32_e32 v211, v211
	v_exp_f32_e32 v212, v212
	v_exp_f32_e32 v213, v213
	v_mul_f32_e32 v124, v124, v140
	v_mul_f32_e32 v125, v125, v141
	v_mul_f32_e32 v126, v126, v142
	v_mul_f32_e32 v127, v127, v143
	v_add_f32_e32 v210, 1.0, v210
	v_add_f32_e32 v211, 1.0, v211
	v_add_f32_e32 v212, 1.0, v212
	v_add_f32_e32 v213, 1.0, v213
	v_rcp_f32_e32 v210, v210
	v_rcp_f32_e32 v211, v211
	v_rcp_f32_e32 v212, v212
	v_rcp_f32_e32 v213, v213
	v_mul_f32_e32 v108, v108, v210
	v_mul_f32_e32 v109, v109, v211
	v_mul_f32_e32 v110, v110, v212
	v_mul_f32_e32 v111, v111, v213
	v_mul_f32_e32 v108, v124, v108
	v_mul_f32_e32 v109, v125, v109
	v_mul_f32_e32 v110, v126, v110
	v_mul_f32_e32 v111, v127, v111
	v_cvt_pk_bf16_f32 v220, v108, v109
	v_cvt_pk_bf16_f32 v221, v110, v111
	ds_write_b64 v195, v[220:221] offset:48
	s_waitcnt lgkmcnt(7)
	ds_read_b128 v[160:163], v194 offset:256
	v_mul_f32_e32 v48, v48, v144
	v_mul_f32_e32 v49, v49, v145
	v_mul_f32_e32 v50, v50, v146
	v_mul_f32_e32 v51, v51, v147
	v_mul_f32_e32 v210, 0xbfb8aa3b, v48
	v_mul_f32_e32 v211, 0xbfb8aa3b, v49
	v_mul_f32_e32 v212, 0xbfb8aa3b, v50
	v_mul_f32_e32 v213, 0xbfb8aa3b, v51
	v_exp_f32_e32 v210, v210
	v_exp_f32_e32 v211, v211
	v_exp_f32_e32 v212, v212
	v_exp_f32_e32 v213, v213
	v_mul_f32_e32 v32, v32, v144
	v_mul_f32_e32 v33, v33, v145
	v_mul_f32_e32 v34, v34, v146
	v_mul_f32_e32 v35, v35, v147
	v_add_f32_e32 v210, 1.0, v210
	v_add_f32_e32 v211, 1.0, v211
	v_add_f32_e32 v212, 1.0, v212
	v_add_f32_e32 v213, 1.0, v213
	v_rcp_f32_e32 v210, v210
	v_rcp_f32_e32 v211, v211
	v_rcp_f32_e32 v212, v212
	v_rcp_f32_e32 v213, v213
	v_mul_f32_e32 v48, v48, v210
	v_mul_f32_e32 v49, v49, v211
	v_mul_f32_e32 v50, v50, v212
	v_mul_f32_e32 v51, v51, v213
	v_mul_f32_e32 v48, v32, v48
	v_mul_f32_e32 v49, v33, v49
	v_mul_f32_e32 v50, v34, v50
	v_mul_f32_e32 v51, v35, v51
	v_cvt_pk_bf16_f32 v214, v48, v49
	v_cvt_pk_bf16_f32 v215, v50, v51
	ds_write_b64 v195, v[214:215] offset:64
	s_waitcnt lgkmcnt(7)
	ds_read_b128 v[164:167], v194 offset:288
	v_mul_f32_e32 v52, v52, v148
	v_mul_f32_e32 v53, v53, v149
	v_mul_f32_e32 v54, v54, v150
	v_mul_f32_e32 v55, v55, v151
	v_mul_f32_e32 v210, 0xbfb8aa3b, v52
	v_mul_f32_e32 v211, 0xbfb8aa3b, v53
	v_mul_f32_e32 v212, 0xbfb8aa3b, v54
	v_mul_f32_e32 v213, 0xbfb8aa3b, v55
	v_exp_f32_e32 v210, v210
	v_exp_f32_e32 v211, v211
	v_exp_f32_e32 v212, v212
	v_exp_f32_e32 v213, v213
	v_mul_f32_e32 v36, v36, v148
	v_mul_f32_e32 v37, v37, v149
	v_mul_f32_e32 v38, v38, v150
	v_mul_f32_e32 v39, v39, v151
	v_add_f32_e32 v210, 1.0, v210
	v_add_f32_e32 v211, 1.0, v211
	v_add_f32_e32 v212, 1.0, v212
	v_add_f32_e32 v213, 1.0, v213
	v_rcp_f32_e32 v210, v210
	v_rcp_f32_e32 v211, v211
	v_rcp_f32_e32 v212, v212
	v_rcp_f32_e32 v213, v213
	v_mul_f32_e32 v52, v52, v210
	v_mul_f32_e32 v53, v53, v211
	v_mul_f32_e32 v54, v54, v212
	v_mul_f32_e32 v55, v55, v213
	v_mul_f32_e32 v52, v36, v52
	v_mul_f32_e32 v53, v37, v53
	v_mul_f32_e32 v54, v38, v54
	v_mul_f32_e32 v55, v39, v55
	v_cvt_pk_bf16_f32 v216, v52, v53
	v_cvt_pk_bf16_f32 v217, v54, v55
	ds_write_b64 v195, v[216:217] offset:80
	s_waitcnt lgkmcnt(7)
	ds_read_b128 v[168:171], v194 offset:320
	v_mul_f32_e32 v56, v56, v152
	v_mul_f32_e32 v57, v57, v153
	v_mul_f32_e32 v58, v58, v154
	v_mul_f32_e32 v59, v59, v155
	v_mul_f32_e32 v210, 0xbfb8aa3b, v56
	v_mul_f32_e32 v211, 0xbfb8aa3b, v57
	v_mul_f32_e32 v212, 0xbfb8aa3b, v58
	v_mul_f32_e32 v213, 0xbfb8aa3b, v59
	v_exp_f32_e32 v210, v210
	v_exp_f32_e32 v211, v211
	v_exp_f32_e32 v212, v212
	v_exp_f32_e32 v213, v213
	v_mul_f32_e32 v40, v40, v152
	v_mul_f32_e32 v41, v41, v153
	v_mul_f32_e32 v42, v42, v154
	v_mul_f32_e32 v43, v43, v155
	v_add_f32_e32 v210, 1.0, v210
	v_add_f32_e32 v211, 1.0, v211
	v_add_f32_e32 v212, 1.0, v212
	v_add_f32_e32 v213, 1.0, v213
	v_rcp_f32_e32 v210, v210
	v_rcp_f32_e32 v211, v211
	v_rcp_f32_e32 v212, v212
	v_rcp_f32_e32 v213, v213
	v_mul_f32_e32 v56, v56, v210
	v_mul_f32_e32 v57, v57, v211
	v_mul_f32_e32 v58, v58, v212
	v_mul_f32_e32 v59, v59, v213
	v_mul_f32_e32 v56, v40, v56
	v_mul_f32_e32 v57, v41, v57
	v_mul_f32_e32 v58, v42, v58
	v_mul_f32_e32 v59, v43, v59
	v_cvt_pk_bf16_f32 v218, v56, v57
	v_cvt_pk_bf16_f32 v219, v58, v59
	ds_write_b64 v195, v[218:219] offset:96
	s_waitcnt lgkmcnt(7)
	ds_read_b128 v[172:175], v194 offset:352
	v_mul_f32_e32 v60, v60, v156
	v_mul_f32_e32 v61, v61, v157
	v_mul_f32_e32 v62, v62, v158
	v_mul_f32_e32 v63, v63, v159
	v_mul_f32_e32 v210, 0xbfb8aa3b, v60
	v_mul_f32_e32 v211, 0xbfb8aa3b, v61
	v_mul_f32_e32 v212, 0xbfb8aa3b, v62
	v_mul_f32_e32 v213, 0xbfb8aa3b, v63
	v_exp_f32_e32 v210, v210
	v_exp_f32_e32 v211, v211
	v_exp_f32_e32 v212, v212
	v_exp_f32_e32 v213, v213
	v_mul_f32_e32 v44, v44, v156
	v_mul_f32_e32 v45, v45, v157
	v_mul_f32_e32 v46, v46, v158
	v_mul_f32_e32 v47, v47, v159
	v_add_f32_e32 v210, 1.0, v210
	v_add_f32_e32 v211, 1.0, v211
	v_add_f32_e32 v212, 1.0, v212
	v_add_f32_e32 v213, 1.0, v213
	v_rcp_f32_e32 v210, v210
	v_rcp_f32_e32 v211, v211
	v_rcp_f32_e32 v212, v212
	v_rcp_f32_e32 v213, v213
	v_mul_f32_e32 v60, v60, v210
	v_mul_f32_e32 v61, v61, v211
	v_mul_f32_e32 v62, v62, v212
	v_mul_f32_e32 v63, v63, v213
	v_mul_f32_e32 v60, v44, v60
	v_mul_f32_e32 v61, v45, v61
	v_mul_f32_e32 v62, v46, v62
	v_mul_f32_e32 v63, v47, v63
	v_cvt_pk_bf16_f32 v220, v60, v61
	v_cvt_pk_bf16_f32 v221, v62, v63
	ds_write_b64 v195, v[220:221] offset:112
	s_waitcnt lgkmcnt(7)
	ds_read_b128 v[176:179], v194 offset:384
	v_mul_f32_e32 v64, v64, v160
	v_mul_f32_e32 v65, v65, v161
	v_mul_f32_e32 v66, v66, v162
	v_mul_f32_e32 v67, v67, v163
	v_mul_f32_e32 v210, 0xbfb8aa3b, v64
	v_mul_f32_e32 v211, 0xbfb8aa3b, v65
	v_mul_f32_e32 v212, 0xbfb8aa3b, v66
	v_mul_f32_e32 v213, 0xbfb8aa3b, v67
	v_exp_f32_e32 v210, v210
	v_exp_f32_e32 v211, v211
	v_exp_f32_e32 v212, v212
	v_exp_f32_e32 v213, v213
	v_mul_f32_e32 v80, v80, v160
	v_mul_f32_e32 v81, v81, v161
	v_mul_f32_e32 v82, v82, v162
	v_mul_f32_e32 v83, v83, v163
	v_add_f32_e32 v210, 1.0, v210
	v_add_f32_e32 v211, 1.0, v211
	v_add_f32_e32 v212, 1.0, v212
	v_add_f32_e32 v213, 1.0, v213
	v_rcp_f32_e32 v210, v210
	v_rcp_f32_e32 v211, v211
	v_rcp_f32_e32 v212, v212
	v_rcp_f32_e32 v213, v213
	v_mul_f32_e32 v64, v64, v210
	v_mul_f32_e32 v65, v65, v211
	v_mul_f32_e32 v66, v66, v212
	v_mul_f32_e32 v67, v67, v213
	v_mul_f32_e32 v64, v80, v64
	v_mul_f32_e32 v65, v81, v65
	v_mul_f32_e32 v66, v82, v66
	v_mul_f32_e32 v67, v83, v67
	v_cvt_pk_bf16_f32 v214, v64, v65
	v_cvt_pk_bf16_f32 v215, v66, v67
	ds_write_b64 v195, v[214:215] offset:128
	s_waitcnt lgkmcnt(7)
	ds_read_b128 v[180:183], v194 offset:416
	v_mul_f32_e32 v68, v68, v164
	v_mul_f32_e32 v69, v69, v165
	v_mul_f32_e32 v70, v70, v166
	v_mul_f32_e32 v71, v71, v167
	v_mul_f32_e32 v210, 0xbfb8aa3b, v68
	v_mul_f32_e32 v211, 0xbfb8aa3b, v69
	v_mul_f32_e32 v212, 0xbfb8aa3b, v70
	v_mul_f32_e32 v213, 0xbfb8aa3b, v71
	v_exp_f32_e32 v210, v210
	v_exp_f32_e32 v211, v211
	v_exp_f32_e32 v212, v212
	v_exp_f32_e32 v213, v213
	v_mul_f32_e32 v84, v84, v164
	v_mul_f32_e32 v85, v85, v165
	v_mul_f32_e32 v86, v86, v166
	v_mul_f32_e32 v87, v87, v167
	v_add_f32_e32 v210, 1.0, v210
	v_add_f32_e32 v211, 1.0, v211
	v_add_f32_e32 v212, 1.0, v212
	v_add_f32_e32 v213, 1.0, v213
	v_rcp_f32_e32 v210, v210
	v_rcp_f32_e32 v211, v211
	v_rcp_f32_e32 v212, v212
	v_rcp_f32_e32 v213, v213
	v_mul_f32_e32 v68, v68, v210
	v_mul_f32_e32 v69, v69, v211
	v_mul_f32_e32 v70, v70, v212
	v_mul_f32_e32 v71, v71, v213
	v_mul_f32_e32 v68, v84, v68
	v_mul_f32_e32 v69, v85, v69
	v_mul_f32_e32 v70, v86, v70
	v_mul_f32_e32 v71, v87, v71
	v_cvt_pk_bf16_f32 v216, v68, v69
	v_cvt_pk_bf16_f32 v217, v70, v71
	ds_write_b64 v195, v[216:217] offset:144
	s_waitcnt lgkmcnt(7)
	ds_read_b128 v[184:187], v194 offset:448
	v_mul_f32_e32 v72, v72, v168
	v_mul_f32_e32 v73, v73, v169
	v_mul_f32_e32 v74, v74, v170
	v_mul_f32_e32 v75, v75, v171
	v_mul_f32_e32 v210, 0xbfb8aa3b, v72
	v_mul_f32_e32 v211, 0xbfb8aa3b, v73
	v_mul_f32_e32 v212, 0xbfb8aa3b, v74
	v_mul_f32_e32 v213, 0xbfb8aa3b, v75
	v_exp_f32_e32 v210, v210
	v_exp_f32_e32 v211, v211
	v_exp_f32_e32 v212, v212
	v_exp_f32_e32 v213, v213
	v_mul_f32_e32 v88, v88, v168
	v_mul_f32_e32 v89, v89, v169
	v_mul_f32_e32 v90, v90, v170
	v_mul_f32_e32 v91, v91, v171
	v_add_f32_e32 v210, 1.0, v210
	v_add_f32_e32 v211, 1.0, v211
	v_add_f32_e32 v212, 1.0, v212
	v_add_f32_e32 v213, 1.0, v213
	v_rcp_f32_e32 v210, v210
	v_rcp_f32_e32 v211, v211
	v_rcp_f32_e32 v212, v212
	v_rcp_f32_e32 v213, v213
	v_mul_f32_e32 v72, v72, v210
	v_mul_f32_e32 v73, v73, v211
	v_mul_f32_e32 v74, v74, v212
	v_mul_f32_e32 v75, v75, v213
	v_mul_f32_e32 v72, v88, v72
	v_mul_f32_e32 v73, v89, v73
	v_mul_f32_e32 v74, v90, v74
	v_mul_f32_e32 v75, v91, v75
	v_cvt_pk_bf16_f32 v218, v72, v73
	v_cvt_pk_bf16_f32 v219, v74, v75
	ds_write_b64 v195, v[218:219] offset:160
	s_waitcnt lgkmcnt(7)
	ds_read_b128 v[188:191], v194 offset:480
	v_mul_f32_e32 v76, v76, v172
	v_mul_f32_e32 v77, v77, v173
	v_mul_f32_e32 v78, v78, v174
	v_mul_f32_e32 v79, v79, v175
	v_mul_f32_e32 v210, 0xbfb8aa3b, v76
	v_mul_f32_e32 v211, 0xbfb8aa3b, v77
	v_mul_f32_e32 v212, 0xbfb8aa3b, v78
	v_mul_f32_e32 v213, 0xbfb8aa3b, v79
	v_exp_f32_e32 v210, v210
	v_exp_f32_e32 v211, v211
	v_exp_f32_e32 v212, v212
	v_exp_f32_e32 v213, v213
	v_mul_f32_e32 v92, v92, v172
	v_mul_f32_e32 v93, v93, v173
	v_mul_f32_e32 v94, v94, v174
	v_mul_f32_e32 v95, v95, v175
	v_add_f32_e32 v210, 1.0, v210
	v_add_f32_e32 v211, 1.0, v211
	v_add_f32_e32 v212, 1.0, v212
	v_add_f32_e32 v213, 1.0, v213
	v_rcp_f32_e32 v210, v210
	v_rcp_f32_e32 v211, v211
	v_rcp_f32_e32 v212, v212
	v_rcp_f32_e32 v213, v213
	v_mul_f32_e32 v76, v76, v210
	v_mul_f32_e32 v77, v77, v211
	v_mul_f32_e32 v78, v78, v212
	v_mul_f32_e32 v79, v79, v213
	v_mul_f32_e32 v76, v92, v76
	v_mul_f32_e32 v77, v93, v77
	v_mul_f32_e32 v78, v94, v78
	v_mul_f32_e32 v79, v95, v79
	v_cvt_pk_bf16_f32 v220, v76, v77
	v_cvt_pk_bf16_f32 v221, v78, v79
	ds_write_b64 v195, v[220:221] offset:176
	s_waitcnt lgkmcnt(7)
	v_mul_f32_e32 v16, v16, v176
	v_mul_f32_e32 v17, v17, v177
	v_mul_f32_e32 v18, v18, v178
	v_mul_f32_e32 v19, v19, v179
	v_mul_f32_e32 v210, 0xbfb8aa3b, v16
	v_mul_f32_e32 v211, 0xbfb8aa3b, v17
	v_mul_f32_e32 v212, 0xbfb8aa3b, v18
	v_mul_f32_e32 v213, 0xbfb8aa3b, v19
	v_exp_f32_e32 v210, v210
	v_exp_f32_e32 v211, v211
	v_exp_f32_e32 v212, v212
	v_exp_f32_e32 v213, v213
	v_mul_f32_e32 v0, v0, v176
	v_mul_f32_e32 v1, v1, v177
	v_mul_f32_e32 v2, v2, v178
	v_mul_f32_e32 v3, v3, v179
	v_add_f32_e32 v210, 1.0, v210
	v_add_f32_e32 v211, 1.0, v211
	v_add_f32_e32 v212, 1.0, v212
	v_add_f32_e32 v213, 1.0, v213
	v_rcp_f32_e32 v210, v210
	v_rcp_f32_e32 v211, v211
	v_rcp_f32_e32 v212, v212
	v_rcp_f32_e32 v213, v213
	v_mul_f32_e32 v16, v16, v210
	v_mul_f32_e32 v17, v17, v211
	v_mul_f32_e32 v18, v18, v212
	v_mul_f32_e32 v19, v19, v213
	v_mul_f32_e32 v16, v0, v16
	v_mul_f32_e32 v17, v1, v17
	v_mul_f32_e32 v18, v2, v18
	v_mul_f32_e32 v19, v3, v19
	v_cvt_pk_bf16_f32 v214, v16, v17
	v_cvt_pk_bf16_f32 v215, v18, v19
	ds_write_b64 v195, v[214:215] offset:192
	s_waitcnt lgkmcnt(6)
	v_mul_f32_e32 v20, v20, v180
	v_mul_f32_e32 v21, v21, v181
	v_mul_f32_e32 v22, v22, v182
	v_mul_f32_e32 v23, v23, v183
	v_mul_f32_e32 v210, 0xbfb8aa3b, v20
	v_mul_f32_e32 v211, 0xbfb8aa3b, v21
	v_mul_f32_e32 v212, 0xbfb8aa3b, v22
	v_mul_f32_e32 v213, 0xbfb8aa3b, v23
	v_exp_f32_e32 v210, v210
	v_exp_f32_e32 v211, v211
	v_exp_f32_e32 v212, v212
	v_exp_f32_e32 v213, v213
	v_mul_f32_e32 v4, v4, v180
	v_mul_f32_e32 v5, v5, v181
	v_mul_f32_e32 v6, v6, v182
	v_mul_f32_e32 v7, v7, v183
	v_add_f32_e32 v210, 1.0, v210
	v_add_f32_e32 v211, 1.0, v211
	v_add_f32_e32 v212, 1.0, v212
	v_add_f32_e32 v213, 1.0, v213
	v_rcp_f32_e32 v210, v210
	v_rcp_f32_e32 v211, v211
	v_rcp_f32_e32 v212, v212
	v_rcp_f32_e32 v213, v213
	v_mul_f32_e32 v20, v20, v210
	v_mul_f32_e32 v21, v21, v211
	v_mul_f32_e32 v22, v22, v212
	v_mul_f32_e32 v23, v23, v213
	v_mul_f32_e32 v20, v4, v20
	v_mul_f32_e32 v21, v5, v21
	v_mul_f32_e32 v22, v6, v22
	v_mul_f32_e32 v23, v7, v23
	v_cvt_pk_bf16_f32 v216, v20, v21
	v_cvt_pk_bf16_f32 v217, v22, v23
	ds_write_b64 v195, v[216:217] offset:208
	s_waitcnt lgkmcnt(5)
	v_mul_f32_e32 v24, v24, v184
	v_mul_f32_e32 v25, v25, v185
	v_mul_f32_e32 v26, v26, v186
	v_mul_f32_e32 v27, v27, v187
	v_mul_f32_e32 v210, 0xbfb8aa3b, v24
	v_mul_f32_e32 v211, 0xbfb8aa3b, v25
	v_mul_f32_e32 v212, 0xbfb8aa3b, v26
	v_mul_f32_e32 v213, 0xbfb8aa3b, v27
	v_exp_f32_e32 v210, v210
	v_exp_f32_e32 v211, v211
	v_exp_f32_e32 v212, v212
	v_exp_f32_e32 v213, v213
	v_mul_f32_e32 v8, v8, v184
	v_mul_f32_e32 v9, v9, v185
	v_mul_f32_e32 v10, v10, v186
	v_mul_f32_e32 v11, v11, v187
	v_add_f32_e32 v210, 1.0, v210
	v_add_f32_e32 v211, 1.0, v211
	v_add_f32_e32 v212, 1.0, v212
	v_add_f32_e32 v213, 1.0, v213
	v_rcp_f32_e32 v210, v210
	v_rcp_f32_e32 v211, v211
	v_rcp_f32_e32 v212, v212
	v_rcp_f32_e32 v213, v213
	v_mul_f32_e32 v24, v24, v210
	v_mul_f32_e32 v25, v25, v211
	v_mul_f32_e32 v26, v26, v212
	v_mul_f32_e32 v27, v27, v213
	v_mul_f32_e32 v24, v8, v24
	v_mul_f32_e32 v25, v9, v25
	v_mul_f32_e32 v26, v10, v26
	v_mul_f32_e32 v27, v11, v27
	v_cvt_pk_bf16_f32 v218, v24, v25
	v_cvt_pk_bf16_f32 v219, v26, v27
	ds_write_b64 v195, v[218:219] offset:224
	s_waitcnt lgkmcnt(4)
	v_mul_f32_e32 v28, v28, v188
	v_mul_f32_e32 v29, v29, v189
	v_mul_f32_e32 v30, v30, v190
	v_mul_f32_e32 v31, v31, v191
	v_mul_f32_e32 v210, 0xbfb8aa3b, v28
	v_mul_f32_e32 v211, 0xbfb8aa3b, v29
	v_mul_f32_e32 v212, 0xbfb8aa3b, v30
	v_mul_f32_e32 v213, 0xbfb8aa3b, v31
	v_exp_f32_e32 v210, v210
	v_exp_f32_e32 v211, v211
	v_exp_f32_e32 v212, v212
	v_exp_f32_e32 v213, v213
	v_mul_f32_e32 v12, v12, v188
	v_mul_f32_e32 v13, v13, v189
	v_mul_f32_e32 v14, v14, v190
	v_mul_f32_e32 v15, v15, v191
	v_add_f32_e32 v210, 1.0, v210
	v_add_f32_e32 v211, 1.0, v211
	v_add_f32_e32 v212, 1.0, v212
	v_add_f32_e32 v213, 1.0, v213
	v_rcp_f32_e32 v210, v210
	v_rcp_f32_e32 v211, v211
	v_rcp_f32_e32 v212, v212
	v_rcp_f32_e32 v213, v213
	v_mul_f32_e32 v28, v28, v210
	v_mul_f32_e32 v29, v29, v211
	v_mul_f32_e32 v30, v30, v212
	v_mul_f32_e32 v31, v31, v213
	v_mul_f32_e32 v28, v12, v28
	v_mul_f32_e32 v29, v13, v29
	v_mul_f32_e32 v30, v14, v30
	v_mul_f32_e32 v31, v15, v31
	v_cvt_pk_bf16_f32 v220, v28, v29
	v_cvt_pk_bf16_f32 v221, v30, v31
	ds_write_b64 v195, v[220:221] offset:240
	s_waitcnt lgkmcnt(0)
	ds_read_b64_tr_b16 v[0:1], v196 offset:0
	ds_read_b64_tr_b16 v[2:3], v196 offset:1056
	ds_read_b64_tr_b16 v[4:5], v196 offset:32
	ds_read_b64_tr_b16 v[6:7], v196 offset:1088
	ds_read_b64_tr_b16 v[8:9], v196 offset:64
	ds_read_b64_tr_b16 v[10:11], v196 offset:1120
	ds_read_b64_tr_b16 v[12:13], v196 offset:96
	ds_read_b64_tr_b16 v[14:15], v196 offset:1152
	s_waitcnt lgkmcnt(6)
	ds_read_b64_tr_b16 v[16:17], v196 offset:128
	ds_read_b64_tr_b16 v[18:19], v196 offset:1184
	global_store_dwordx4 v197, v[0:3], s[42:43]
	v_add_u32_e32 v197, 0x16000, v197
	s_waitcnt lgkmcnt(6)
	ds_read_b64_tr_b16 v[20:21], v196 offset:160
	ds_read_b64_tr_b16 v[22:23], v196 offset:1216
	global_store_dwordx4 v197, v[4:7], s[42:43]
	v_add_u32_e32 v197, 0x16000, v197
	s_waitcnt lgkmcnt(6)
	ds_read_b64_tr_b16 v[24:25], v196 offset:192
	ds_read_b64_tr_b16 v[26:27], v196 offset:1248
	global_store_dwordx4 v197, v[8:11], s[42:43]
	v_add_u32_e32 v197, 0x16000, v197
	s_waitcnt lgkmcnt(6)
	ds_read_b64_tr_b16 v[28:29], v196 offset:224
	ds_read_b64_tr_b16 v[30:31], v196 offset:1280
	global_store_dwordx4 v197, v[12:15], s[42:43]
	v_add_u32_e32 v197, 0x16000, v197
	s_waitcnt lgkmcnt(6)
	global_store_dwordx4 v197, v[16:19], s[42:43]
	v_add_u32_e32 v197, 0x16000, v197
	s_waitcnt lgkmcnt(4)
	global_store_dwordx4 v197, v[20:23], s[42:43]
	v_add_u32_e32 v197, 0x16000, v197
	s_waitcnt lgkmcnt(2)
	global_store_dwordx4 v197, v[24:27], s[42:43]
	v_add_u32_e32 v197, 0x16000, v197
	s_waitcnt lgkmcnt(0)
	global_store_dwordx4 v197, v[28:31], s[42:43]
	s_add_i32 s26, s26, s92
	s_cmpk_lt_i32 s26, 0x596
	s_cbranch_scc0 .LBB0_541

.LBB0_3203:
	s_lshl_b32 s0, s50, 1
	s_or_b32 s5, s33, s0
	s_waitcnt vmcnt(0)
	v_and_b32_e32 v157, 0xff, v208
	s_lshr_b32 s12, s50, 2
	s_mul_i32 s4, s5, 0x28a000
	s_add_u32 s0, s60, s4
	v_or_b32_e32 v171, 0x100, v157
	s_addc_u32 s1, s61, 0
	v_lshlrev_b32_e32 v0, 4, v157
	v_lshlrev_b32_e32 v1, 4, v171
	v_or_b32_e32 v172, 0x200, v157
	v_or_b32_e32 v8, 0x300, v208
	s_barrier
	global_load_dwordx4 v[96:99], v0, s[0:1]
	global_load_dwordx4 v[100:103], v1, s[0:1]
	v_lshlrev_b32_e32 v1, 4, v172
	v_lshlrev_b32_e32 v4, 4, v8
	v_or_b32_e32 v9, 0x400, v157
	v_or_b32_e32 v10, 0x500, v157
	global_load_dwordx4 v[104:107], v4, s[0:1]
	v_lshlrev_b32_e32 v5, 4, v9
	global_load_dwordx4 v[108:111], v1, s[0:1]
	global_load_dwordx4 v[112:115], v5, s[0:1]
	v_lshlrev_b32_e32 v1, 4, v10
	v_or_b32_e32 v11, 0x600, v157
	v_or_b32_e32 v12, 0x700, v208
	v_or_b32_e32 v13, 0x800, v157
	v_lshlrev_b32_e32 v5, 4, v11
	global_load_dwordx4 v[116:119], v1, s[0:1]
	global_load_dwordx4 v[120:123], v5, s[0:1]
	v_lshlrev_b32_e32 v6, 4, v12
	v_lshlrev_b32_e32 v1, 4, v13
	v_or_b32_e32 v14, 0x900, v157
	global_load_dwordx4 v[124:127], v6, s[0:1]
	global_load_dwordx4 v[128:131], v1, s[0:1]
	v_lshlrev_b32_e32 v1, 4, v14
	global_load_dwordx4 v[132:135], v1, s[0:1]
	v_and_b32_e32 v156, 56, v3
	v_lshrrev_b32_e32 v8, 3, v8
	v_lshlrev_b32_e32 v3, 1, v156
	v_mul_u32_u24_e32 v8, 0x88, v8
	v_lshrrev_b32_e32 v9, 3, v9
	v_mul_u32_u24_e32 v15, 0x88, v170
	v_add3_u32 v175, s36, v8, v3
	v_mul_u32_u24_e32 v8, 0x88, v9
	v_lshrrev_b32_e32 v12, 3, v12
	v_add3_u32 v174, s36, v15, v3
	v_lshrrev_b32_e32 v173, 3, v171
	v_lshrrev_b32_e32 v15, 3, v172
	v_lshrrev_b32_e32 v10, 3, v10
	v_lshrrev_b32_e32 v11, 3, v11
	v_lshrrev_b32_e32 v13, 3, v13
	v_add3_u32 v179, s36, v8, v3
	v_lshrrev_b32_e32 v8, 3, v14
	s_mov_b32 s1, 0
	s_mul_i32 s0, s5, 0x41
	v_mul_u32_u24_e32 v12, 0x88, v12
	v_mul_u32_u24_e32 v16, 0x88, v173
	v_mul_u32_u24_e32 v15, 0x88, v15
	v_mul_u32_u24_e32 v9, 0x88, v10
	v_mul_u32_u24_e32 v10, 0x88, v11
	v_mul_u32_u24_e32 v11, 0x88, v13
	v_mul_u32_u24_e32 v8, 0x88, v8
	v_add3_u32 v176, s36, v12, v3
	s_lshl_b64 s[0:1], s[0:1], 2
	v_add3_u32 v177, s36, v16, v3
	v_add3_u32 v178, s36, v15, v3
	v_add3_u32 v180, s36, v9, v3
	v_add3_u32 v181, s36, v10, v3
	v_add3_u32 v182, s36, v11, v3
	v_add3_u32 v183, s36, v8, v3
	v_mbcnt_hi_u32_b32 v3, -1, v209
	s_add_u32 s0, s90, s0
	v_and_b32_e32 v9, 64, v3
	s_addc_u32 s1, s91, s1
	v_xor_b32_e32 v8, 1, v3
	v_add_u32_e32 v9, 64, v9
	s_add_u32 s0, s0, 0x13d6000
	v_cmp_lt_i32_e32 vcc, v8, v9
	s_addc_u32 s1, s1, 0
	s_lshl_b32 s5, s5, 7
	v_cndmask_b32_e32 v8, v3, v8, vcc
	v_lshlrev_b32_e32 v188, 2, v8
	v_xor_b32_e32 v8, 2, v3
	s_and_b32 s5, s5, 0x380
	v_mov_b32_e32 v1, 0
	v_and_b32_e32 v11, 48, v213
	v_cmp_lt_i32_e32 vcc, v8, v9
	s_add_u32 s6, s58, s5
	s_addc_u32 s7, s59, 0
	v_cndmask_b32_e32 v3, v3, v8, vcc
	v_lshlrev_b32_e32 v8, 1, v11
	v_mov_b32_e32 v9, v1
	v_lshl_add_u64 v[158:159], s[6:7], 0, v[8:9]
	s_add_u32 s6, s90, s5
	s_addc_u32 s7, s91, 0
	v_bfe_u32 v10, v208, 2, 6
	v_lshlrev_b32_e32 v189, 2, v3
	v_and_b32_e32 v185, 0x60, v2
	v_lshl_add_u64 v[2:3], s[6:7], 0, v[8:9]
	s_mov_b64 s[6:7], 0x241ba00
	v_or_b32_e32 v186, v185, v211
	v_and_b32_e32 v12, 4, v212
	v_lshl_add_u64 v[160:161], v[2:3], 0, s[6:7]
	v_mul_u32_u24_e32 v3, 0x104, v10
	v_lshlrev_b32_e32 v2, 2, v11
	v_readlane_b32 s16, v239, 4
	s_add_u32 s4, s90, s4
	s_movk_i32 s8, 0x88
	v_mov_b32_e32 v5, v1
	v_mov_b32_e32 v7, v1
	v_lshl_add_u32 v13, v12, 1, s36
	v_mul_u32_u24_e32 v187, 0x44, v211
	v_lshl_add_u32 v16, v186, 2, s36
	v_mul_u32_u24_e32 v17, 0x104, v12
	v_add3_u32 v192, s36, v3, v2
	v_mov_b32_e32 v3, v1
	v_readlane_b32 s17, v239, 5
	s_addc_u32 s5, s91, 0
	v_mov_b32_e32 v14, v1
	v_mov_b32_e32 v15, v1
	v_subrev_u32_e32 v184, 48, v10
	s_movk_i32 s2, 0x80
	v_mad_u32_u24 v190, v186, s8, v13
	v_lshl_add_u32 v191, v187, 1, v13
	v_readlane_b32 s18, v239, 6
	v_lshl_add_u64 v[162:163], s[16:17], 0, v[2:3]
	v_lshl_add_u64 v[164:165], s[4:5], 0, v[0:1]
	v_lshl_add_u64 v[166:167], s[4:5], 0, v[4:5]
	v_lshl_add_u64 v[168:169], s[4:5], 0, v[6:7]
	v_mov_b32_e32 v0, v1
	v_mov_b32_e32 v2, v1
	v_mov_b32_e32 v4, v1
	v_mov_b32_e32 v6, v1
	v_mov_b32_e32 v8, v1
	v_mov_b32_e32 v10, v1
	v_mov_b32_e32 v11, v1
	v_mov_b32_e32 v12, v1
	v_mov_b32_e32 v13, v1
	v_add_u32_e32 v193, v16, v17
	v_mov_b64_e32 v[30:31], v[14:15]
	v_mov_b64_e32 v[46:47], v[14:15]
	v_cmp_gt_u32_e64 s[2:3], s2, v157
	s_mulk_i32 s12, 0x1010
	s_mov_b64 s[6:7], 0
	s_mov_b32 s13, 0x6d45000
	s_mov_b32 s15, 0x6d49000
	s_mov_b32 s16, 0x6d4a000
	s_mov_b32 s17, 0x6d4b000
	v_mov_b32_e32 v194, 0x358637bd
	s_mov_b32 s18, 0x800000
	v_mov_b64_e32 v[28:29], v[12:13]
	v_mov_b64_e32 v[26:27], v[10:11]
	v_mov_b64_e32 v[24:25], v[8:9]
	v_mov_b64_e32 v[22:23], v[6:7]
	v_mov_b64_e32 v[20:21], v[4:5]
	v_mov_b64_e32 v[18:19], v[2:3]
	v_mov_b64_e32 v[16:17], v[0:1]
	v_mov_b64_e32 v[44:45], v[12:13]
	v_mov_b64_e32 v[42:43], v[10:11]
	v_mov_b64_e32 v[40:41], v[8:9]
	v_mov_b64_e32 v[38:39], v[6:7]
	v_mov_b64_e32 v[36:37], v[4:5]
	v_mov_b64_e32 v[34:35], v[2:3]
	v_mov_b64_e32 v[32:33], v[0:1]
	global_load_dwordx4 v[214:217], v[162:163], off
	global_load_dwordx4 v[218:221], v[162:163], off offset:16
	global_load_dwordx4 v[222:225], v[162:163], off offset:48
	global_load_dwordx4 v[226:229], v[162:163], off offset:32
	global_load_dword v230, v1, s[0:1]
	s_waitcnt vmcnt(9)
	ds_write2_b64 v174, v[96:97], v[98:99] offset1:1
	s_waitcnt vmcnt(8)
	ds_write2_b64 v177, v[100:101], v[102:103] offset1:1
	s_waitcnt vmcnt(6)
	ds_write2_b64 v178, v[108:109], v[110:111] offset1:1
	ds_write2_b64 v175, v[104:105], v[106:107] offset1:1
	s_waitcnt vmcnt(5)
	ds_write2_b64 v179, v[112:113], v[114:115] offset1:1
	s_waitcnt vmcnt(4)
	ds_write2_b64 v180, v[116:117], v[118:119] offset1:1
	s_waitcnt vmcnt(3)
	ds_write2_b64 v181, v[120:121], v[122:123] offset1:1
	s_waitcnt vmcnt(2)
	ds_write2_b64 v176, v[124:125], v[126:127] offset1:1
	s_waitcnt vmcnt(1)
	ds_write2_b64 v182, v[128:129], v[130:131] offset1:1
	s_waitcnt vmcnt(0)
	ds_write2_b64 v183, v[132:133], v[134:135] offset1:1
	s_waitcnt lgkmcnt(0)
	s_barrier
	v_readlane_b32 s19, v239, 7
	v_readlane_b32 s20, v239, 8
	v_readlane_b32 s21, v239, 9
	v_readlane_b32 s22, v239, 10
	v_readlane_b32 s23, v239, 11
	v_readlane_b32 s24, v239, 12
	v_readlane_b32 s25, v239, 13
	v_readlane_b32 s26, v239, 14
	v_readlane_b32 s27, v239, 15
	v_readlane_b32 s28, v239, 16
	v_readlane_b32 s29, v239, 17
	v_readlane_b32 s30, v239, 18
	v_readlane_b32 s31, v239, 19
	s_branch .LBB0_3205
.LBB0_3204:
	v_mov_b32_e32 v230, v231
	s_add_u32 s6, s6, 0xa000
	s_addc_u32 s7, s7, 0
	s_add_u32 s0, s0, 4
	s_addc_u32 s1, s1, 0
	s_cmp_lg_u32 s6, 0x28a000
	v_add_u32_e32 v184, 64, v184
	s_waitcnt lgkmcnt(0)
	s_barrier
	s_cbranch_scc0 .LBB0_3215
.LBB0_3205:
	global_load_dword v231, v1, s[0:1] offset:4
	v_cmp_lt_i32_e64 s[4:5], -1, v184
	v_add_u32_e32 v0, s12, v184
	v_mov_b32_e32 v2, 0
	v_mov_b32_e32 v3, 0
	v_mov_b32_e32 v4, 0
	v_mov_b32_e32 v5, 0
	v_mov_b32_e32 v6, 0
	v_mov_b32_e32 v7, 0
	v_mov_b32_e32 v8, 0
	v_mov_b32_e32 v9, 0
	s_and_saveexec_b64 s[8:9], s[4:5]
	s_cbranch_execz .LBB0_3207
	v_lshlrev_b64 v[2:3], 10, v[0:1]
	v_lshl_add_u64 v[6:7], v[158:159], 0, v[2:3]
	global_load_dwordx4 v[2:5], v[6:7], off offset:16
	s_nop 0
	global_load_dwordx4 v[6:9], v[6:7], off

.LBB0_3209:
	s_and_saveexec_b64 s[10:11], s[2:3]
	s_cbranch_execz .LBB0_3211
	ds_read2_b64 v[48:51], v190 offset1:2
	v_add_u32_e32 v15, 0x2000, v191
	ds_read2_b64 v[52:55], v190 offset0:4 offset1:6
	v_cvt_pk_bf16_f32 v136, v16, v17
	v_cvt_pk_bf16_f32 v137, v18, v19
	s_waitcnt lgkmcnt(1)
	v_lshlrev_b32_e32 v64, 16, v48
	v_and_b32_e32 v65, 0xffff0000, v48
	v_lshlrev_b32_e32 v66, 16, v49
	v_and_b32_e32 v67, 0xffff0000, v49
	v_lshlrev_b32_e32 v68, 16, v50
	v_and_b32_e32 v69, 0xffff0000, v50
	v_lshlrev_b32_e32 v70, 16, v51
	v_and_b32_e32 v71, 0xffff0000, v51
	ds_read2_b64 v[48:51], v15 offset0:64 offset1:66
	v_cvt_pk_bf16_f32 v138, v20, v21
	v_cvt_pk_bf16_f32 v139, v22, v23
	s_waitcnt lgkmcnt(1)
	v_lshlrev_b32_e32 v72, 16, v52
	v_and_b32_e32 v73, 0xffff0000, v52
	v_lshlrev_b32_e32 v74, 16, v53
	v_and_b32_e32 v75, 0xffff0000, v53
	v_lshlrev_b32_e32 v76, 16, v54
	v_and_b32_e32 v77, 0xffff0000, v54
	v_lshlrev_b32_e32 v78, 16, v55
	v_and_b32_e32 v79, 0xffff0000, v55
	ds_read2_b64 v[52:55], v15 offset0:68 offset1:70
	v_cvt_pk_bf16_f32 v10, v24, v25
	s_waitcnt lgkmcnt(1)
	v_mfma_f32_32x32x16_bf16 v[64:79], v[48:51], v[136:139], v[64:79]
	ds_read2_b64 v[48:51], v190 offset0:8 offset1:10
	v_cvt_pk_bf16_f32 v11, v26, v27
	v_cvt_pk_bf16_f32 v12, v28, v29
	v_cvt_pk_bf16_f32 v13, v30, v31
	ds_read2_b64 v[56:59], v15 offset0:72 offset1:74
	s_waitcnt lgkmcnt(1)
	v_lshlrev_b32_e32 v80, 16, v48
	v_and_b32_e32 v81, 0xffff0000, v48
	v_mfma_f32_32x32x16_bf16 v[64:79], v[52:55], v[10:13], v[64:79]
	ds_read2_b64 v[52:55], v190 offset0:12 offset1:14
	ds_read2_b64 v[60:63], v15 offset0:76 offset1:78
	v_add_u32_e32 v15, 0x3000, v191
	v_lshlrev_b32_e32 v82, 16, v49
	v_and_b32_e32 v83, 0xffff0000, v49
	v_lshlrev_b32_e32 v84, 16, v50
	v_and_b32_e32 v85, 0xffff0000, v50
	v_lshlrev_b32_e32 v86, 16, v51
	v_and_b32_e32 v87, 0xffff0000, v51
	ds_read2_b64 v[48:51], v15 offset0:96 offset1:98
	s_waitcnt lgkmcnt(2)
	v_lshlrev_b32_e32 v88, 16, v52
	v_and_b32_e32 v89, 0xffff0000, v52
	v_lshlrev_b32_e32 v90, 16, v53
	v_and_b32_e32 v91, 0xffff0000, v53
	v_lshlrev_b32_e32 v92, 16, v54
	v_and_b32_e32 v93, 0xffff0000, v54
	v_lshlrev_b32_e32 v94, 16, v55
	v_and_b32_e32 v95, 0xffff0000, v55
	v_cvt_pk_bf16_f32 v140, v32, v33
	v_cvt_pk_bf16_f32 v141, v34, v35
	s_waitcnt lgkmcnt(0)
	v_mfma_f32_32x32x16_bf16 v[80:95], v[48:51], v[136:139], v[80:95]
	ds_read2_b64 v[48:51], v15 offset0:100 offset1:102
	v_cvt_pk_bf16_f32 v142, v36, v37
	v_cvt_pk_bf16_f32 v143, v38, v39
	v_cvt_pk_bf16_f32 v148, v40, v41
	v_cvt_pk_bf16_f32 v149, v42, v43
	v_cvt_pk_bf16_f32 v150, v44, v45
	v_cvt_pk_bf16_f32 v151, v46, v47
	s_waitcnt lgkmcnt(0)
	v_mfma_f32_32x32x16_bf16 v[80:95], v[48:51], v[10:13], v[80:95]
	ds_read2_b64 v[48:51], v15 offset0:104 offset1:106
	v_add_u32_e32 v195, 0x6000, v191
	ds_read2_b64 v[152:155], v195 offset0:192 offset1:194
	s_waitcnt lgkmcnt(1)
	v_mfma_f32_32x32x16_bf16 v[80:95], v[48:51], v[140:143], v[80:95]
	ds_read2_b64 v[48:51], v15 offset0:108 offset1:110
	v_add_u32_e32 v15, 0x4000, v191
	v_mfma_f32_32x32x16_bf16 v[64:79], v[56:59], v[140:143], v[64:79]
	s_waitcnt lgkmcnt(0)
	v_mfma_f32_32x32x16_bf16 v[80:95], v[48:51], v[148:151], v[80:95]
	ds_read2_b64 v[48:51], v15 offset0:128 offset1:130
	v_mfma_f32_32x32x16_bf16 v[64:79], v[60:63], v[148:151], v[64:79]
	s_nop 9
	v_cvt_pk_bf16_f32 v80, v80, v81
	v_cvt_pk_bf16_f32 v81, v82, v83
	v_cvt_pk_bf16_f32 v82, v84, v85
	v_cvt_pk_bf16_f32 v83, v86, v87
	v_cvt_pk_bf16_f32 v84, v88, v89
	v_cvt_pk_bf16_f32 v85, v90, v91
	v_cvt_pk_bf16_f32 v86, v92, v93
	s_waitcnt lgkmcnt(0)
	v_mfma_f32_32x32x16_bf16 v[48:63], v[48:51], v[136:139], 0
	v_cvt_pk_bf16_f32 v144, v64, v65
	v_cvt_pk_bf16_f32 v145, v66, v67
	v_cvt_pk_bf16_f32 v146, v68, v69
	v_cvt_pk_bf16_f32 v147, v70, v71
	ds_read2_b64 v[64:67], v15 offset0:132 offset1:134
	v_cvt_pk_bf16_f32 v87, v94, v95
	v_add_u32_e32 v92, 0x7000, v191
	v_mfma_f32_32x32x16_bf16 v[48:63], v[152:155], v[144:147], v[48:63]
	v_cvt_pk_bf16_f32 v152, v72, v73
	v_cvt_pk_bf16_f32 v153, v74, v75
	v_cvt_pk_bf16_f32 v154, v76, v77
	v_cvt_pk_bf16_f32 v155, v78, v79
	ds_read2_b64 v[88:91], v92 offset0:224 offset1:226
	s_waitcnt lgkmcnt(1)
	v_mfma_f32_32x32x16_bf16 v[48:63], v[64:67], v[10:13], v[48:63]
	ds_read2_b64 v[64:67], v195 offset0:196 offset1:198
	s_waitcnt lgkmcnt(0)
	v_mfma_f32_32x32x16_bf16 v[48:63], v[64:67], v[152:155], v[48:63]
	ds_read2_b64 v[64:67], v15 offset0:136 offset1:138
	s_waitcnt lgkmcnt(0)
	v_mfma_f32_32x32x16_bf16 v[48:63], v[64:67], v[140:143], v[48:63]
	ds_read2_b64 v[64:67], v195 offset0:200 offset1:202
	s_waitcnt lgkmcnt(0)
	v_mfma_f32_32x32x16_bf16 v[48:63], v[64:67], v[80:83], v[48:63]
	ds_read2_b64 v[64:67], v15 offset0:140 offset1:142
	v_add_u32_e32 v15, 0x5000, v191
	s_waitcnt lgkmcnt(0)
	v_mfma_f32_32x32x16_bf16 v[48:63], v[64:67], v[148:151], v[48:63]
	ds_read2_b64 v[64:67], v195 offset0:204 offset1:206
	s_waitcnt lgkmcnt(0)
	v_mfma_f32_32x32x16_bf16 v[48:63], v[64:67], v[84:87], v[48:63]
	ds_read2_b64 v[64:67], v15 offset0:160 offset1:162
	s_waitcnt lgkmcnt(0)
	v_mfma_f32_32x32x16_bf16 v[64:79], v[64:67], v[136:139], 0
	v_mfma_f32_32x32x16_bf16 v[64:79], v[88:91], v[144:147], v[64:79]
	ds_read2_b64 v[88:91], v15 offset0:164 offset1:166
	s_waitcnt lgkmcnt(0)
	v_mfma_f32_32x32x16_bf16 v[64:79], v[88:91], v[10:13], v[64:79]
	ds_read2_b64 v[10:13], v92 offset0:228 offset1:230
	s_waitcnt lgkmcnt(0)
	v_mfma_f32_32x32x16_bf16 v[64:79], v[10:13], v[152:155], v[64:79]
	ds_read2_b64 v[10:13], v15 offset0:168 offset1:170
	s_waitcnt lgkmcnt(0)
	v_mfma_f32_32x32x16_bf16 v[64:79], v[10:13], v[140:143], v[64:79]
	ds_read2_b64 v[10:13], v92 offset0:232 offset1:234
	s_waitcnt lgkmcnt(0)
	v_mfma_f32_32x32x16_bf16 v[64:79], v[10:13], v[80:83], v[64:79]
	ds_read2_b64 v[10:13], v15 offset0:172 offset1:174
	v_add_u32_e32 v15, 0x8800, v191
	v_mul_f32_e64 v30, v30, v230
	v_mul_f32_e64 v31, v31, v230
	v_pk_mul_f32 v[28:29], v[28:29], v[230:231] op_sel_hi:[1,0]
	v_pk_mul_f32 v[26:27], v[26:27], v[230:231] op_sel_hi:[1,0]
	v_pk_mul_f32 v[24:25], v[24:25], v[230:231] op_sel_hi:[1,0]
	v_pk_mul_f32 v[22:23], v[22:23], v[230:231] op_sel_hi:[1,0]
	s_waitcnt lgkmcnt(0)
	v_mfma_f32_32x32x16_bf16 v[64:79], v[10:13], v[148:151], v[64:79]
	ds_read2_b64 v[10:13], v92 offset0:236 offset1:238
	v_mul_f32_e64 v20, v20, v230
	v_mul_f32_e64 v21, v21, v230
	v_mul_f32_e64 v18, v18, v230
	v_mul_f32_e64 v19, v19, v230
	v_pk_mul_f32 v[16:17], v[16:17], v[230:231] op_sel_hi:[1,0]
	v_pk_mul_f32 v[46:47], v[46:47], v[230:231] op_sel_hi:[1,0]
	v_pk_mul_f32 v[44:45], v[44:45], v[230:231] op_sel_hi:[1,0]
	v_pk_mul_f32 v[42:43], v[42:43], v[230:231] op_sel_hi:[1,0]
	s_waitcnt lgkmcnt(0)
	v_mfma_f32_32x32x16_bf16 v[64:79], v[10:13], v[84:87], v[64:79]
	ds_read2_b64 v[10:13], v15 offset1:2
	v_mul_f32_e64 v40, v40, v230
	v_mul_f32_e64 v41, v41, v230
	v_mul_f32_e64 v38, v38, v230
	v_mul_f32_e64 v39, v39, v230
	v_pk_mul_f32 v[36:37], v[36:37], v[230:231] op_sel_hi:[1,0]
	v_pk_mul_f32 v[34:35], v[34:35], v[230:231] op_sel_hi:[1,0]
	v_pk_mul_f32 v[32:33], v[32:33], v[230:231] op_sel_hi:[1,0]
	v_add_u32_e32 v14, 0x9800, v191
	s_waitcnt lgkmcnt(0)
	v_mfma_f32_32x32x16_bf16 v[16:31], v[10:13], v[144:147], v[16:31]
	ds_read2_b64 v[10:13], v15 offset0:4 offset1:6
	ds_read2_b64 v[88:91], v15 offset0:8 offset1:10
	ds_read2_b64 v[92:95], v15 offset0:12 offset1:14
	s_waitcnt lgkmcnt(2)
	v_mfma_f32_32x32x16_bf16 v[16:31], v[10:13], v[152:155], v[16:31]
	s_waitcnt lgkmcnt(1)
	v_mfma_f32_32x32x16_bf16 v[16:31], v[88:91], v[80:83], v[16:31]
	ds_read2_b64 v[10:13], v14 offset0:32 offset1:34
	ds_read2_b64 v[88:91], v14 offset0:36 offset1:38
	ds_read2_b64 v[136:139], v14 offset0:40 offset1:42
	ds_read2_b64 v[140:143], v14 offset0:44 offset1:46
	v_add_u32_e32 v14, 0xa800, v193
	ds_write2_b32 v14, v48, v49 offset0:128 offset1:193
	v_add_u32_e32 v14, 0xac00, v193
	ds_write2_b32 v14, v50, v51 offset0:2 offset1:67
	v_add_u32_e32 v14, 0xb000, v193
	ds_write2_b32 v14, v52, v53 offset0:136 offset1:201
	s_waitcnt lgkmcnt(6)
	v_mfma_f32_32x32x16_bf16 v[32:47], v[10:13], v[144:147], v[32:47]
	v_add_u32_e32 v10, 0xbc00, v193
	ds_write2_b32 v10, v58, v59 offset0:18 offset1:83
	v_add_u32_e32 v10, 0xc000, v193
	ds_write2_b32 v10, v60, v61 offset0:152 offset1:217
	v_add_u32_e32 v10, 0xc400, v193
	ds_write2_b32 v10, v62, v63 offset0:26 offset1:91
	v_add_u32_e32 v10, 0xc800, v193
	s_waitcnt lgkmcnt(8)
	v_mfma_f32_32x32x16_bf16 v[32:47], v[88:91], v[152:155], v[32:47]
	ds_write2_b32 v10, v64, v65 offset0:160 offset1:225
	v_add_u32_e32 v10, 0xcc00, v193
	ds_write2_b32 v10, v66, v67 offset0:34 offset1:99
	v_add_u32_e32 v10, 0xd000, v193
	ds_write2_b32 v10, v68, v69 offset0:168 offset1:233
	v_add_u32_e32 v10, 0xd400, v193
	ds_write2_b32 v10, v70, v71 offset0:42 offset1:107
	s_waitcnt lgkmcnt(11)
	v_mfma_f32_32x32x16_bf16 v[32:47], v[136:139], v[80:83], v[32:47]
	v_add_u32_e32 v10, 0xd800, v193
	ds_write2_b32 v10, v72, v73 offset0:176 offset1:241
	v_add_u32_e32 v10, 0xdc00, v193
	v_add_u32_e32 v14, 0xb400, v193
	ds_write2_b32 v10, v74, v75 offset0:50 offset1:115
	v_add_u32_e32 v10, 0xe000, v193
	ds_write2_b32 v14, v54, v55 offset0:10 offset1:75
	v_mfma_f32_32x32x16_bf16 v[16:31], v[92:95], v[84:87], v[16:31]
	v_add_u32_e32 v14, 0xb800, v193
	ds_write2_b32 v10, v76, v77 offset0:184 offset1:249
	v_add_u32_e32 v10, 0xe400, v193
	ds_write2_b32 v14, v56, v57 offset0:144 offset1:209
	ds_write2_b32 v10, v78, v79 offset0:58 offset1:123
	s_waitcnt lgkmcnt(14)
	v_mfma_f32_32x32x16_bf16 v[32:47], v[140:143], v[84:87], v[32:47]
.LBB0_3211:
	s_or_b64 exec, exec, s[10:11]
	v_add_u32_e32 v10, 0xaa00, v192
	s_waitcnt lgkmcnt(0)
	s_barrier
	v_add_u32_e32 v11, 0xaa08, v192
	v_add_u32_e32 v12, 0xaa10, v192
	ds_read2_b32 v[48:49], v10 offset1:1
	ds_read2_b32 v[50:51], v11 offset1:1
	ds_read2_b32 v[52:53], v12 offset1:1
	v_add_u32_e32 v10, 0xaa18, v192
	ds_read2_b32 v[54:55], v10 offset1:1
	s_waitcnt lgkmcnt(3)
	v_pk_mul_f32 v[58:59], v[48:49], v[48:49]
	s_waitcnt lgkmcnt(2)
	v_pk_mul_f32 v[60:61], v[50:51], v[50:51]
	v_add_f32_e32 v58, v58, v59
	v_add_f32_e32 v58, v58, v60
	s_waitcnt lgkmcnt(1)
	v_pk_mul_f32 v[62:63], v[52:53], v[52:53]
	v_add_f32_e32 v58, v58, v61
	v_add_u32_e32 v10, 0xaa20, v192
	v_add_u32_e32 v11, 0xaa28, v192
	v_add_u32_e32 v12, 0xaa30, v192
	v_add_u32_e32 v64, 0xaa38, v192
	v_add_f32_e32 v58, v58, v62
	ds_read2_b32 v[56:57], v10 offset1:1
	s_cmp_eq_u32 s6, 0x280000
	s_cbranch_scc1 .Lscan_zw0
	s_waitcnt vmcnt(10)
	s_branch .Lscan_zw1

.Lscan_zw1:
	ds_read2_b32 v[14:15], v11 offset1:1
	ds_read2_b32 v[12:13], v12 offset1:1
	ds_read2_b32 v[10:11], v64 offset1:1
	s_waitcnt lgkmcnt(4)
	v_pk_mul_f32 v[64:65], v[54:55], v[54:55]
	v_add_f32_e32 v58, v58, v63
	v_add_f32_e32 v58, v58, v64
	s_waitcnt lgkmcnt(3)
	v_pk_mul_f32 v[66:67], v[56:57], v[56:57]
	v_add_f32_e32 v58, v58, v65
	v_add_f32_e32 v58, v58, v66
	s_waitcnt lgkmcnt(2)
	v_pk_mul_f32 v[68:69], v[14:15], v[14:15]
	v_add_f32_e32 v58, v58, v67
	v_add_f32_e32 v58, v58, v68
	s_waitcnt lgkmcnt(1)
	v_pk_mul_f32 v[70:71], v[12:13], v[12:13]
	v_add_f32_e32 v58, v58, v69
	v_add_f32_e32 v58, v58, v70
	s_waitcnt lgkmcnt(0)
	v_pk_mul_f32 v[72:73], v[10:11], v[10:11]
	v_add_f32_e32 v58, v58, v71
	v_add_f32_e32 v58, v58, v72
	v_add_f32_e32 v58, v58, v73
	ds_bpermute_b32 v59, v188, v58
	s_waitcnt lgkmcnt(0)
	v_add_f32_e32 v58, v58, v59
	ds_bpermute_b32 v59, v189, v58
	s_and_saveexec_b64 s[10:11], s[4:5]
	s_cbranch_execz .Lscan_nostore
	s_waitcnt lgkmcnt(0)
	v_add_f32_e32 v80, v58, v59
	v_lshlrev_b32_e32 v76, 16, v8
	v_and_b32_e32 v77, 0xffff0000, v8
	v_lshlrev_b32_e32 v8, 16, v9
	v_and_b32_e32 v9, 0xffff0000, v9
	v_lshlrev_b32_e32 v78, 16, v2
	v_and_b32_e32 v79, 0xffff0000, v2
	v_fmamk_f32 v2, v80, 0x3c800000, v194
	v_mul_f32_e32 v84, 0xbfb8aa3b, v76
	v_mul_f32_e32 v85, 0xbfb8aa3b, v77
	v_mul_f32_e32 v86, 0xbfb8aa3b, v8
	v_mul_f32_e32 v87, 0xbfb8aa3b, v9
	v_mul_f32_e32 v90, 0x4b800000, v2
	v_exp_f32_e32 v84, v84
	v_exp_f32_e32 v85, v85
	v_cmp_gt_f32_e32 vcc, s18, v2
	v_exp_f32_e32 v86, v86
	v_exp_f32_e32 v87, v87
	v_cndmask_b32_e32 v2, v2, v90, vcc
	v_rsq_f32_e32 v2, v2
	v_lshlrev_b32_e32 v58, 16, v6
	v_and_b32_e32 v59, 0xffff0000, v6
	v_lshlrev_b32_e32 v6, 16, v7
	v_and_b32_e32 v7, 0xffff0000, v7
	v_mul_f32_e32 v80, 0xbfb8aa3b, v58
	v_mul_f32_e32 v81, 0xbfb8aa3b, v59
	v_mul_f32_e32 v82, 0xbfb8aa3b, v6
	v_mul_f32_e32 v83, 0xbfb8aa3b, v7
	v_add_f32_e32 v84, 1.0, v84
	v_add_f32_e32 v85, 1.0, v85
	v_exp_f32_e32 v80, v80
	v_exp_f32_e32 v81, v81
	v_exp_f32_e32 v82, v82
	v_exp_f32_e32 v83, v83
	v_add_f32_e32 v86, 1.0, v86
	v_add_f32_e32 v87, 1.0, v87
	v_rcp_f32_e32 v84, v84
	v_rcp_f32_e32 v85, v85
	v_mul_f32_e32 v88, 0xbfb8aa3b, v78
	v_mul_f32_e32 v89, 0xbfb8aa3b, v79
	v_rcp_f32_e32 v86, v86
	v_rcp_f32_e32 v87, v87
	v_mul_f32_e32 v90, 0x45800000, v2
	v_exp_f32_e32 v88, v88
	v_exp_f32_e32 v89, v89
	v_cndmask_b32_e32 v90, v2, v90, vcc
	v_pk_mul_f32 v[52:53], v[52:53], v[90:91] op_sel_hi:[1,0]
	v_add_f32_e32 v80, 1.0, v80
	v_add_f32_e32 v81, 1.0, v81
	v_add_f32_e32 v82, 1.0, v82
	v_add_f32_e32 v83, 1.0, v83
	v_pk_mul_f32 v[54:55], v[54:55], v[90:91] op_sel_hi:[1,0]
	v_pk_mul_f32 v[76:77], v[84:85], v[76:77]
	v_rcp_f32_e32 v80, v80
	v_rcp_f32_e32 v81, v81
	v_rcp_f32_e32 v82, v82
	v_rcp_f32_e32 v83, v83
	v_pk_mul_f32 v[8:9], v[86:87], v[8:9]
	v_add_f32_e32 v88, 1.0, v88
	v_add_f32_e32 v89, 1.0, v89
	v_rcp_f32_e32 v88, v88
	v_rcp_f32_e32 v89, v89
	v_pk_mul_f32 v[48:49], v[48:49], v[90:91] op_sel_hi:[1,0]
	v_pk_mul_f32 v[50:51], v[50:51], v[90:91] op_sel_hi:[1,0]
	v_pk_mul_f32 v[58:59], v[80:81], v[58:59]
	v_pk_mul_f32 v[6:7], v[82:83], v[6:7]
	v_pk_mul_f32 v[56:57], v[56:57], v[90:91] op_sel_hi:[1,0]
	v_pk_mul_f32 v[14:15], v[14:15], v[90:91] op_sel_hi:[1,0]
	v_pk_mul_f32 v[12:13], v[12:13], v[90:91] op_sel_hi:[1,0]
	v_pk_mul_f32 v[10:11], v[10:11], v[90:91] op_sel_hi:[1,0]
	v_pk_mul_f32 v[48:49], v[48:49], v[214:215]
	v_pk_mul_f32 v[52:53], v[52:53], v[218:219]
	v_pk_mul_f32 v[54:55], v[54:55], v[220:221]
	v_pk_mul_f32 v[52:53], v[76:77], v[52:53]
	v_pk_mul_f32 v[54:55], v[8:9], v[54:55]
	v_cvt_pk_bf16_f32 v8, v52, v53
	v_lshlrev_b32_e32 v52, 16, v3
	v_and_b32_e32 v53, 0xffff0000, v3
	v_mul_f32_e32 v2, 0xbfb8aa3b, v52
	v_cvt_pk_bf16_f32 v9, v54, v55
	v_exp_f32_e32 v54, v2
	v_mul_f32_e32 v2, 0xbfb8aa3b, v53
	v_pk_mul_f32 v[50:51], v[50:51], v[216:217]
	v_exp_f32_e32 v55, v2
	v_pk_mul_f32 v[48:49], v[58:59], v[48:49]
	v_pk_mul_f32 v[50:51], v[6:7], v[50:51]
	v_cvt_pk_bf16_f32 v6, v48, v49
	v_cvt_pk_bf16_f32 v7, v50, v51
	v_pk_mul_f32 v[48:49], v[56:57], v[226:227]
	v_pk_mul_f32 v[50:51], v[88:89], v[78:79]
	v_pk_mul_f32 v[14:15], v[14:15], v[228:229]
	v_pk_mul_f32 v[2:3], v[50:51], v[48:49]
	v_lshlrev_b32_e32 v50, 16, v4
	v_add_f32_e32 v48, 1.0, v54
	v_add_f32_e32 v49, 1.0, v55
	v_cvt_pk_bf16_f32 v2, v2, v3
	v_and_b32_e32 v51, 0xffff0000, v4
	v_mul_f32_e32 v3, 0xbfb8aa3b, v50
	v_rcp_f32_e32 v48, v48
	v_rcp_f32_e32 v49, v49
	v_exp_f32_e32 v3, v3
	v_mul_f32_e32 v4, 0xbfb8aa3b, v51
	v_exp_f32_e32 v4, v4
	v_pk_mul_f32 v[48:49], v[48:49], v[52:53]
	v_add_f32_e32 v3, 1.0, v3
	v_pk_mul_f32 v[14:15], v[48:49], v[14:15]
	v_rcp_f32_e32 v48, v3
	v_add_f32_e32 v3, 1.0, v4
	v_rcp_f32_e32 v49, v3
	v_cvt_pk_bf16_f32 v3, v14, v15
	v_pk_mul_f32 v[12:13], v[12:13], v[222:223]
	v_pk_mul_f32 v[10:11], v[10:11], v[224:225]
	v_pk_mul_f32 v[14:15], v[48:49], v[50:51]
	v_lshlrev_b32_e32 v48, 16, v5
	v_and_b32_e32 v49, 0xffff0000, v5
	v_mul_f32_e32 v4, 0xbfb8aa3b, v48
	v_exp_f32_e32 v50, v4
	v_mul_f32_e32 v4, 0xbfb8aa3b, v49
	v_exp_f32_e32 v51, v4
	v_pk_mul_f32 v[4:5], v[14:15], v[12:13]
	v_add_f32_e32 v12, 1.0, v50
	v_rcp_f32_e32 v12, v12
	v_add_f32_e32 v13, 1.0, v51
	v_rcp_f32_e32 v13, v13
	v_cvt_pk_bf16_f32 v4, v4, v5
	v_pk_mul_f32 v[12:13], v[12:13], v[48:49]
	s_nop 0
	v_pk_mul_f32 v[10:11], v[12:13], v[10:11]
	s_nop 0
	v_cvt_pk_bf16_f32 v5, v10, v11
	v_lshlrev_b64 v[10:11], 10, v[0:1]
	v_lshl_add_u64 v[10:11], v[160:161], 0, v[10:11]
	global_store_dwordx4 v[10:11], v[6:9], off
	global_store_dwordx4 v[10:11], v[2:5], off offset:16
	s_waitcnt vmcnt(2)
	s_branch .LBB0_3213
.Lscan_nostore:
	s_waitcnt vmcnt(0)
.LBB0_3213:
	s_or_b64 exec, exec, s[10:11]
	s_andn2_b64 vcc, exec, s[8:9]
	s_cbranch_vccnz .LBB0_3204
	ds_write2_b64 v174, v[96:97], v[98:99] offset1:1
	ds_write2_b64 v177, v[100:101], v[102:103] offset1:1
	ds_write2_b64 v178, v[108:109], v[110:111] offset1:1
	ds_write2_b64 v175, v[104:105], v[106:107] offset1:1
	ds_write2_b64 v179, v[112:113], v[114:115] offset1:1
	ds_write2_b64 v180, v[116:117], v[118:119] offset1:1
	ds_write2_b64 v181, v[120:121], v[122:123] offset1:1
	ds_write2_b64 v176, v[124:125], v[126:127] offset1:1
	ds_write2_b64 v182, v[128:129], v[130:131] offset1:1
	ds_write2_b64 v183, v[132:133], v[134:135] offset1:1
	s_branch .LBB0_3204

.LBB0_4464:
	s_waitcnt vmcnt(0)
	v_and_b32_e32 v198, 31, v208
	v_bfe_u32 v199, v208, 5, 1
	v_lshrrev_b32_e32 v204, 6, v208
	v_lshrrev_b32_e32 v205, 8, v208
	v_lshlrev_b32_e32 v194, 9, v205
	v_lshl_add_u32 v194, v199, 4, v194
	v_add_u32_e32 v194, 0x24000, v194
	ds_read_b128 v[128:131], v194 offset:0
	ds_read_b128 v[132:135], v194 offset:32
	ds_read_b128 v[136:139], v194 offset:64
	ds_read_b128 v[140:143], v194 offset:96
	v_mul_u32_u24_e32 v195, 0x2100, v204
	v_mul_u32_u24_e32 v210, 0x108, v198
	v_add_u32_e32 v211, v195, v210
	v_lshl_add_u32 v211, v199, 3, v211
	v_bfe_u32 v212, v208, 4, 2
	v_bfe_u32 v213, v208, 2, 2
	v_lshl_add_u32 v213, v212, 3, v213
	v_mul_u32_u24_e32 v213, 0x108, v213
	v_and_b32_e32 v210, 3, v208
	v_lshl_add_u32 v213, v210, 3, v213
	v_add_u32_e32 v196, v195, v213
	v_mov_b32_e32 v195, v211
	s_mul_i32 s8, s0, 0x1600
	s_lshl_b32 s9, s29, 8
	s_add_i32 s8, s8, s9
	v_and_b32_e32 v210, 15, v208
	v_lshl_add_u32 v210, v205, 7, v210
	v_mul_u32_u24_e32 v210, 0x1600, v210
	v_and_b32_e32 v211, 3, v204
	v_lshlrev_b32_e32 v211, 6, v211
	v_lshl_add_u32 v211, v212, 4, v211
	v_add3_u32 v197, v210, v211, s8
	s_waitcnt lgkmcnt(3)
	ds_read_b128 v[144:147], v194 offset:128
	v_mul_f32_e32 v96, v96, v128
	v_mul_f32_e32 v97, v97, v129
	v_mul_f32_e32 v98, v98, v130
	v_mul_f32_e32 v99, v99, v131
	v_mul_f32_e32 v210, 0xbfb8aa3b, v96
	v_mul_f32_e32 v211, 0xbfb8aa3b, v97
	v_mul_f32_e32 v212, 0xbfb8aa3b, v98
	v_mul_f32_e32 v213, 0xbfb8aa3b, v99
	v_exp_f32_e32 v210, v210
	v_exp_f32_e32 v211, v211
	v_exp_f32_e32 v212, v212
	v_exp_f32_e32 v213, v213
	v_mul_f32_e32 v112, v112, v128
	v_mul_f32_e32 v113, v113, v129
	v_mul_f32_e32 v114, v114, v130
	v_mul_f32_e32 v115, v115, v131
	v_add_f32_e32 v210, 1.0, v210
	v_add_f32_e32 v211, 1.0, v211
	v_add_f32_e32 v212, 1.0, v212
	v_add_f32_e32 v213, 1.0, v213
	v_rcp_f32_e32 v210, v210
	v_rcp_f32_e32 v211, v211
	v_rcp_f32_e32 v212, v212
	v_rcp_f32_e32 v213, v213
	v_mul_f32_e32 v96, v96, v210
	v_mul_f32_e32 v97, v97, v211
	v_mul_f32_e32 v98, v98, v212
	v_mul_f32_e32 v99, v99, v213
	v_mul_f32_e32 v96, v112, v96
	v_mul_f32_e32 v97, v113, v97
	v_mul_f32_e32 v98, v114, v98
	v_mul_f32_e32 v99, v115, v99
	v_cvt_pk_bf16_f32 v214, v96, v97
	v_cvt_pk_bf16_f32 v215, v98, v99
	ds_write_b64 v195, v[214:215] offset:0
	s_waitcnt lgkmcnt(4)
	ds_read_b128 v[148:151], v194 offset:160
	v_mul_f32_e32 v100, v100, v132
	v_mul_f32_e32 v101, v101, v133
	v_mul_f32_e32 v102, v102, v134
	v_mul_f32_e32 v103, v103, v135
	v_mul_f32_e32 v210, 0xbfb8aa3b, v100
	v_mul_f32_e32 v211, 0xbfb8aa3b, v101
	v_mul_f32_e32 v212, 0xbfb8aa3b, v102
	v_mul_f32_e32 v213, 0xbfb8aa3b, v103
	v_exp_f32_e32 v210, v210
	v_exp_f32_e32 v211, v211
	v_exp_f32_e32 v212, v212
	v_exp_f32_e32 v213, v213
	v_mul_f32_e32 v116, v116, v132
	v_mul_f32_e32 v117, v117, v133
	v_mul_f32_e32 v118, v118, v134
	v_mul_f32_e32 v119, v119, v135
	v_add_f32_e32 v210, 1.0, v210
	v_add_f32_e32 v211, 1.0, v211
	v_add_f32_e32 v212, 1.0, v212
	v_add_f32_e32 v213, 1.0, v213
	v_rcp_f32_e32 v210, v210
	v_rcp_f32_e32 v211, v211
	v_rcp_f32_e32 v212, v212
	v_rcp_f32_e32 v213, v213
	v_mul_f32_e32 v100, v100, v210
	v_mul_f32_e32 v101, v101, v211
	v_mul_f32_e32 v102, v102, v212
	v_mul_f32_e32 v103, v103, v213
	v_mul_f32_e32 v100, v116, v100
	v_mul_f32_e32 v101, v117, v101
	v_mul_f32_e32 v102, v118, v102
	v_mul_f32_e32 v103, v119, v103
	v_cvt_pk_bf16_f32 v216, v100, v101
	v_cvt_pk_bf16_f32 v217, v102, v103
	ds_write_b64 v195, v[216:217] offset:16
	s_waitcnt lgkmcnt(5)
	ds_read_b128 v[152:155], v194 offset:192
	v_mul_f32_e32 v104, v104, v136
	v_mul_f32_e32 v105, v105, v137
	v_mul_f32_e32 v106, v106, v138
	v_mul_f32_e32 v107, v107, v139
	v_mul_f32_e32 v210, 0xbfb8aa3b, v104
	v_mul_f32_e32 v211, 0xbfb8aa3b, v105
	v_mul_f32_e32 v212, 0xbfb8aa3b, v106
	v_mul_f32_e32 v213, 0xbfb8aa3b, v107
	v_exp_f32_e32 v210, v210
	v_exp_f32_e32 v211, v211
	v_exp_f32_e32 v212, v212
	v_exp_f32_e32 v213, v213
	v_mul_f32_e32 v120, v120, v136
	v_mul_f32_e32 v121, v121, v137
	v_mul_f32_e32 v122, v122, v138
	v_mul_f32_e32 v123, v123, v139
	v_add_f32_e32 v210, 1.0, v210
	v_add_f32_e32 v211, 1.0, v211
	v_add_f32_e32 v212, 1.0, v212
	v_add_f32_e32 v213, 1.0, v213
	v_rcp_f32_e32 v210, v210
	v_rcp_f32_e32 v211, v211
	v_rcp_f32_e32 v212, v212
	v_rcp_f32_e32 v213, v213
	v_mul_f32_e32 v104, v104, v210
	v_mul_f32_e32 v105, v105, v211
	v_mul_f32_e32 v106, v106, v212
	v_mul_f32_e32 v107, v107, v213
	v_mul_f32_e32 v104, v120, v104
	v_mul_f32_e32 v105, v121, v105
	v_mul_f32_e32 v106, v122, v106
	v_mul_f32_e32 v107, v123, v107
	v_cvt_pk_bf16_f32 v218, v104, v105
	v_cvt_pk_bf16_f32 v219, v106, v107
	ds_write_b64 v195, v[218:219] offset:32
	s_waitcnt lgkmcnt(6)
	ds_read_b128 v[156:159], v194 offset:224
	v_mul_f32_e32 v108, v108, v140
	v_mul_f32_e32 v109, v109, v141
	v_mul_f32_e32 v110, v110, v142
	v_mul_f32_e32 v111, v111, v143
	v_mul_f32_e32 v210, 0xbfb8aa3b, v108
	v_mul_f32_e32 v211, 0xbfb8aa3b, v109
	v_mul_f32_e32 v212, 0xbfb8aa3b, v110
	v_mul_f32_e32 v213, 0xbfb8aa3b, v111
	v_exp_f32_e32 v210, v210
	v_exp_f32_e32 v211, v211
	v_exp_f32_e32 v212, v212
	v_exp_f32_e32 v213, v213
	v_mul_f32_e32 v124, v124, v140
	v_mul_f32_e32 v125, v125, v141
	v_mul_f32_e32 v126, v126, v142
	v_mul_f32_e32 v127, v127, v143
	v_add_f32_e32 v210, 1.0, v210
	v_add_f32_e32 v211, 1.0, v211
	v_add_f32_e32 v212, 1.0, v212
	v_add_f32_e32 v213, 1.0, v213
	v_rcp_f32_e32 v210, v210
	v_rcp_f32_e32 v211, v211
	v_rcp_f32_e32 v212, v212
	v_rcp_f32_e32 v213, v213
	v_mul_f32_e32 v108, v108, v210
	v_mul_f32_e32 v109, v109, v211
	v_mul_f32_e32 v110, v110, v212
	v_mul_f32_e32 v111, v111, v213
	v_mul_f32_e32 v108, v124, v108
	v_mul_f32_e32 v109, v125, v109
	v_mul_f32_e32 v110, v126, v110
	v_mul_f32_e32 v111, v127, v111
	v_cvt_pk_bf16_f32 v220, v108, v109
	v_cvt_pk_bf16_f32 v221, v110, v111
	ds_write_b64 v195, v[220:221] offset:48
	s_waitcnt lgkmcnt(7)
	ds_read_b128 v[160:163], v194 offset:256
	v_mul_f32_e32 v48, v48, v144
	v_mul_f32_e32 v49, v49, v145
	v_mul_f32_e32 v50, v50, v146
	v_mul_f32_e32 v51, v51, v147
	v_mul_f32_e32 v210, 0xbfb8aa3b, v48
	v_mul_f32_e32 v211, 0xbfb8aa3b, v49
	v_mul_f32_e32 v212, 0xbfb8aa3b, v50
	v_mul_f32_e32 v213, 0xbfb8aa3b, v51
	v_exp_f32_e32 v210, v210
	v_exp_f32_e32 v211, v211
	v_exp_f32_e32 v212, v212
	v_exp_f32_e32 v213, v213
	v_mul_f32_e32 v32, v32, v144
	v_mul_f32_e32 v33, v33, v145
	v_mul_f32_e32 v34, v34, v146
	v_mul_f32_e32 v35, v35, v147
	v_add_f32_e32 v210, 1.0, v210
	v_add_f32_e32 v211, 1.0, v211
	v_add_f32_e32 v212, 1.0, v212
	v_add_f32_e32 v213, 1.0, v213
	v_rcp_f32_e32 v210, v210
	v_rcp_f32_e32 v211, v211
	v_rcp_f32_e32 v212, v212
	v_rcp_f32_e32 v213, v213
	v_mul_f32_e32 v48, v48, v210
	v_mul_f32_e32 v49, v49, v211
	v_mul_f32_e32 v50, v50, v212
	v_mul_f32_e32 v51, v51, v213
	v_mul_f32_e32 v48, v32, v48
	v_mul_f32_e32 v49, v33, v49
	v_mul_f32_e32 v50, v34, v50
	v_mul_f32_e32 v51, v35, v51
	v_cvt_pk_bf16_f32 v214, v48, v49
	v_cvt_pk_bf16_f32 v215, v50, v51
	ds_write_b64 v195, v[214:215] offset:64
	s_waitcnt lgkmcnt(7)
	ds_read_b128 v[164:167], v194 offset:288
	v_mul_f32_e32 v52, v52, v148
	v_mul_f32_e32 v53, v53, v149
	v_mul_f32_e32 v54, v54, v150
	v_mul_f32_e32 v55, v55, v151
	v_mul_f32_e32 v210, 0xbfb8aa3b, v52
	v_mul_f32_e32 v211, 0xbfb8aa3b, v53
	v_mul_f32_e32 v212, 0xbfb8aa3b, v54
	v_mul_f32_e32 v213, 0xbfb8aa3b, v55
	v_exp_f32_e32 v210, v210
	v_exp_f32_e32 v211, v211
	v_exp_f32_e32 v212, v212
	v_exp_f32_e32 v213, v213
	v_mul_f32_e32 v36, v36, v148
	v_mul_f32_e32 v37, v37, v149
	v_mul_f32_e32 v38, v38, v150
	v_mul_f32_e32 v39, v39, v151
	v_add_f32_e32 v210, 1.0, v210
	v_add_f32_e32 v211, 1.0, v211
	v_add_f32_e32 v212, 1.0, v212
	v_add_f32_e32 v213, 1.0, v213
	v_rcp_f32_e32 v210, v210
	v_rcp_f32_e32 v211, v211
	v_rcp_f32_e32 v212, v212
	v_rcp_f32_e32 v213, v213
	v_mul_f32_e32 v52, v52, v210
	v_mul_f32_e32 v53, v53, v211
	v_mul_f32_e32 v54, v54, v212
	v_mul_f32_e32 v55, v55, v213
	v_mul_f32_e32 v52, v36, v52
	v_mul_f32_e32 v53, v37, v53
	v_mul_f32_e32 v54, v38, v54
	v_mul_f32_e32 v55, v39, v55
	v_cvt_pk_bf16_f32 v216, v52, v53
	v_cvt_pk_bf16_f32 v217, v54, v55
	ds_write_b64 v195, v[216:217] offset:80
	s_waitcnt lgkmcnt(7)
	ds_read_b128 v[168:171], v194 offset:320
	v_mul_f32_e32 v56, v56, v152
	v_mul_f32_e32 v57, v57, v153
	v_mul_f32_e32 v58, v58, v154
	v_mul_f32_e32 v59, v59, v155
	v_mul_f32_e32 v210, 0xbfb8aa3b, v56
	v_mul_f32_e32 v211, 0xbfb8aa3b, v57
	v_mul_f32_e32 v212, 0xbfb8aa3b, v58
	v_mul_f32_e32 v213, 0xbfb8aa3b, v59
	v_exp_f32_e32 v210, v210
	v_exp_f32_e32 v211, v211
	v_exp_f32_e32 v212, v212
	v_exp_f32_e32 v213, v213
	v_mul_f32_e32 v40, v40, v152
	v_mul_f32_e32 v41, v41, v153
	v_mul_f32_e32 v42, v42, v154
	v_mul_f32_e32 v43, v43, v155
	v_add_f32_e32 v210, 1.0, v210
	v_add_f32_e32 v211, 1.0, v211
	v_add_f32_e32 v212, 1.0, v212
	v_add_f32_e32 v213, 1.0, v213
	v_rcp_f32_e32 v210, v210
	v_rcp_f32_e32 v211, v211
	v_rcp_f32_e32 v212, v212
	v_rcp_f32_e32 v213, v213
	v_mul_f32_e32 v56, v56, v210
	v_mul_f32_e32 v57, v57, v211
	v_mul_f32_e32 v58, v58, v212
	v_mul_f32_e32 v59, v59, v213
	v_mul_f32_e32 v56, v40, v56
	v_mul_f32_e32 v57, v41, v57
	v_mul_f32_e32 v58, v42, v58
	v_mul_f32_e32 v59, v43, v59
	v_cvt_pk_bf16_f32 v218, v56, v57
	v_cvt_pk_bf16_f32 v219, v58, v59
	ds_write_b64 v195, v[218:219] offset:96
	s_waitcnt lgkmcnt(7)
	ds_read_b128 v[172:175], v194 offset:352
	v_mul_f32_e32 v60, v60, v156
	v_mul_f32_e32 v61, v61, v157
	v_mul_f32_e32 v62, v62, v158
	v_mul_f32_e32 v63, v63, v159
	v_mul_f32_e32 v210, 0xbfb8aa3b, v60
	v_mul_f32_e32 v211, 0xbfb8aa3b, v61
	v_mul_f32_e32 v212, 0xbfb8aa3b, v62
	v_mul_f32_e32 v213, 0xbfb8aa3b, v63
	v_exp_f32_e32 v210, v210
	v_exp_f32_e32 v211, v211
	v_exp_f32_e32 v212, v212
	v_exp_f32_e32 v213, v213
	v_mul_f32_e32 v44, v44, v156
	v_mul_f32_e32 v45, v45, v157
	v_mul_f32_e32 v46, v46, v158
	v_mul_f32_e32 v47, v47, v159
	v_add_f32_e32 v210, 1.0, v210
	v_add_f32_e32 v211, 1.0, v211
	v_add_f32_e32 v212, 1.0, v212
	v_add_f32_e32 v213, 1.0, v213
	v_rcp_f32_e32 v210, v210
	v_rcp_f32_e32 v211, v211
	v_rcp_f32_e32 v212, v212
	v_rcp_f32_e32 v213, v213
	v_mul_f32_e32 v60, v60, v210
	v_mul_f32_e32 v61, v61, v211
	v_mul_f32_e32 v62, v62, v212
	v_mul_f32_e32 v63, v63, v213
	v_mul_f32_e32 v60, v44, v60
	v_mul_f32_e32 v61, v45, v61
	v_mul_f32_e32 v62, v46, v62
	v_mul_f32_e32 v63, v47, v63
	v_cvt_pk_bf16_f32 v220, v60, v61
	v_cvt_pk_bf16_f32 v221, v62, v63
	ds_write_b64 v195, v[220:221] offset:112
	s_waitcnt lgkmcnt(7)
	ds_read_b128 v[176:179], v194 offset:384
	v_mul_f32_e32 v64, v64, v160
	v_mul_f32_e32 v65, v65, v161
	v_mul_f32_e32 v66, v66, v162
	v_mul_f32_e32 v67, v67, v163
	v_mul_f32_e32 v210, 0xbfb8aa3b, v64
	v_mul_f32_e32 v211, 0xbfb8aa3b, v65
	v_mul_f32_e32 v212, 0xbfb8aa3b, v66
	v_mul_f32_e32 v213, 0xbfb8aa3b, v67
	v_exp_f32_e32 v210, v210
	v_exp_f32_e32 v211, v211
	v_exp_f32_e32 v212, v212
	v_exp_f32_e32 v213, v213
	v_mul_f32_e32 v80, v80, v160
	v_mul_f32_e32 v81, v81, v161
	v_mul_f32_e32 v82, v82, v162
	v_mul_f32_e32 v83, v83, v163
	v_add_f32_e32 v210, 1.0, v210
	v_add_f32_e32 v211, 1.0, v211
	v_add_f32_e32 v212, 1.0, v212
	v_add_f32_e32 v213, 1.0, v213
	v_rcp_f32_e32 v210, v210
	v_rcp_f32_e32 v211, v211
	v_rcp_f32_e32 v212, v212
	v_rcp_f32_e32 v213, v213
	v_mul_f32_e32 v64, v64, v210
	v_mul_f32_e32 v65, v65, v211
	v_mul_f32_e32 v66, v66, v212
	v_mul_f32_e32 v67, v67, v213
	v_mul_f32_e32 v64, v80, v64
	v_mul_f32_e32 v65, v81, v65
	v_mul_f32_e32 v66, v82, v66
	v_mul_f32_e32 v67, v83, v67
	v_cvt_pk_bf16_f32 v214, v64, v65
	v_cvt_pk_bf16_f32 v215, v66, v67
	ds_write_b64 v195, v[214:215] offset:128
	s_waitcnt lgkmcnt(7)
	ds_read_b128 v[180:183], v194 offset:416
	v_mul_f32_e32 v68, v68, v164
	v_mul_f32_e32 v69, v69, v165
	v_mul_f32_e32 v70, v70, v166
	v_mul_f32_e32 v71, v71, v167
	v_mul_f32_e32 v210, 0xbfb8aa3b, v68
	v_mul_f32_e32 v211, 0xbfb8aa3b, v69
	v_mul_f32_e32 v212, 0xbfb8aa3b, v70
	v_mul_f32_e32 v213, 0xbfb8aa3b, v71
	v_exp_f32_e32 v210, v210
	v_exp_f32_e32 v211, v211
	v_exp_f32_e32 v212, v212
	v_exp_f32_e32 v213, v213
	v_mul_f32_e32 v84, v84, v164
	v_mul_f32_e32 v85, v85, v165
	v_mul_f32_e32 v86, v86, v166
	v_mul_f32_e32 v87, v87, v167
	v_add_f32_e32 v210, 1.0, v210
	v_add_f32_e32 v211, 1.0, v211
	v_add_f32_e32 v212, 1.0, v212
	v_add_f32_e32 v213, 1.0, v213
	v_rcp_f32_e32 v210, v210
	v_rcp_f32_e32 v211, v211
	v_rcp_f32_e32 v212, v212
	v_rcp_f32_e32 v213, v213
	v_mul_f32_e32 v68, v68, v210
	v_mul_f32_e32 v69, v69, v211
	v_mul_f32_e32 v70, v70, v212
	v_mul_f32_e32 v71, v71, v213
	v_mul_f32_e32 v68, v84, v68
	v_mul_f32_e32 v69, v85, v69
	v_mul_f32_e32 v70, v86, v70
	v_mul_f32_e32 v71, v87, v71
	v_cvt_pk_bf16_f32 v216, v68, v69
	v_cvt_pk_bf16_f32 v217, v70, v71
	ds_write_b64 v195, v[216:217] offset:144
	s_waitcnt lgkmcnt(7)
	ds_read_b128 v[184:187], v194 offset:448
	v_mul_f32_e32 v72, v72, v168
	v_mul_f32_e32 v73, v73, v169
	v_mul_f32_e32 v74, v74, v170
	v_mul_f32_e32 v75, v75, v171
	v_mul_f32_e32 v210, 0xbfb8aa3b, v72
	v_mul_f32_e32 v211, 0xbfb8aa3b, v73
	v_mul_f32_e32 v212, 0xbfb8aa3b, v74
	v_mul_f32_e32 v213, 0xbfb8aa3b, v75
	v_exp_f32_e32 v210, v210
	v_exp_f32_e32 v211, v211
	v_exp_f32_e32 v212, v212
	v_exp_f32_e32 v213, v213
	v_mul_f32_e32 v88, v88, v168
	v_mul_f32_e32 v89, v89, v169
	v_mul_f32_e32 v90, v90, v170
	v_mul_f32_e32 v91, v91, v171
	v_add_f32_e32 v210, 1.0, v210
	v_add_f32_e32 v211, 1.0, v211
	v_add_f32_e32 v212, 1.0, v212
	v_add_f32_e32 v213, 1.0, v213
	v_rcp_f32_e32 v210, v210
	v_rcp_f32_e32 v211, v211
	v_rcp_f32_e32 v212, v212
	v_rcp_f32_e32 v213, v213
	v_mul_f32_e32 v72, v72, v210
	v_mul_f32_e32 v73, v73, v211
	v_mul_f32_e32 v74, v74, v212
	v_mul_f32_e32 v75, v75, v213
	v_mul_f32_e32 v72, v88, v72
	v_mul_f32_e32 v73, v89, v73
	v_mul_f32_e32 v74, v90, v74
	v_mul_f32_e32 v75, v91, v75
	v_cvt_pk_bf16_f32 v218, v72, v73
	v_cvt_pk_bf16_f32 v219, v74, v75
	ds_write_b64 v195, v[218:219] offset:160
	s_waitcnt lgkmcnt(7)
	ds_read_b128 v[188:191], v194 offset:480
	v_mul_f32_e32 v76, v76, v172
	v_mul_f32_e32 v77, v77, v173
	v_mul_f32_e32 v78, v78, v174
	v_mul_f32_e32 v79, v79, v175
	v_mul_f32_e32 v210, 0xbfb8aa3b, v76
	v_mul_f32_e32 v211, 0xbfb8aa3b, v77
	v_mul_f32_e32 v212, 0xbfb8aa3b, v78
	v_mul_f32_e32 v213, 0xbfb8aa3b, v79
	v_exp_f32_e32 v210, v210
	v_exp_f32_e32 v211, v211
	v_exp_f32_e32 v212, v212
	v_exp_f32_e32 v213, v213
	v_mul_f32_e32 v92, v92, v172
	v_mul_f32_e32 v93, v93, v173
	v_mul_f32_e32 v94, v94, v174
	v_mul_f32_e32 v95, v95, v175
	v_add_f32_e32 v210, 1.0, v210
	v_add_f32_e32 v211, 1.0, v211
	v_add_f32_e32 v212, 1.0, v212
	v_add_f32_e32 v213, 1.0, v213
	v_rcp_f32_e32 v210, v210
	v_rcp_f32_e32 v211, v211
	v_rcp_f32_e32 v212, v212
	v_rcp_f32_e32 v213, v213
	v_mul_f32_e32 v76, v76, v210
	v_mul_f32_e32 v77, v77, v211
	v_mul_f32_e32 v78, v78, v212
	v_mul_f32_e32 v79, v79, v213
	v_mul_f32_e32 v76, v92, v76
	v_mul_f32_e32 v77, v93, v77
	v_mul_f32_e32 v78, v94, v78
	v_mul_f32_e32 v79, v95, v79
	v_cvt_pk_bf16_f32 v220, v76, v77
	v_cvt_pk_bf16_f32 v221, v78, v79
	ds_write_b64 v195, v[220:221] offset:176
	s_waitcnt lgkmcnt(7)
	v_mul_f32_e32 v16, v16, v176
	v_mul_f32_e32 v17, v17, v177
	v_mul_f32_e32 v18, v18, v178
	v_mul_f32_e32 v19, v19, v179
	v_mul_f32_e32 v210, 0xbfb8aa3b, v16
	v_mul_f32_e32 v211, 0xbfb8aa3b, v17
	v_mul_f32_e32 v212, 0xbfb8aa3b, v18
	v_mul_f32_e32 v213, 0xbfb8aa3b, v19
	v_exp_f32_e32 v210, v210
	v_exp_f32_e32 v211, v211
	v_exp_f32_e32 v212, v212
	v_exp_f32_e32 v213, v213
	v_mul_f32_e32 v0, v0, v176
	v_mul_f32_e32 v1, v1, v177
	v_mul_f32_e32 v2, v2, v178
	v_mul_f32_e32 v3, v3, v179
	v_add_f32_e32 v210, 1.0, v210
	v_add_f32_e32 v211, 1.0, v211
	v_add_f32_e32 v212, 1.0, v212
	v_add_f32_e32 v213, 1.0, v213
	v_rcp_f32_e32 v210, v210
	v_rcp_f32_e32 v211, v211
	v_rcp_f32_e32 v212, v212
	v_rcp_f32_e32 v213, v213
	v_mul_f32_e32 v16, v16, v210
	v_mul_f32_e32 v17, v17, v211
	v_mul_f32_e32 v18, v18, v212
	v_mul_f32_e32 v19, v19, v213
	v_mul_f32_e32 v16, v0, v16
	v_mul_f32_e32 v17, v1, v17
	v_mul_f32_e32 v18, v2, v18
	v_mul_f32_e32 v19, v3, v19
	v_cvt_pk_bf16_f32 v214, v16, v17
	v_cvt_pk_bf16_f32 v215, v18, v19
	ds_write_b64 v195, v[214:215] offset:192
	s_waitcnt lgkmcnt(6)
	v_mul_f32_e32 v20, v20, v180
	v_mul_f32_e32 v21, v21, v181
	v_mul_f32_e32 v22, v22, v182
	v_mul_f32_e32 v23, v23, v183
	v_mul_f32_e32 v210, 0xbfb8aa3b, v20
	v_mul_f32_e32 v211, 0xbfb8aa3b, v21
	v_mul_f32_e32 v212, 0xbfb8aa3b, v22
	v_mul_f32_e32 v213, 0xbfb8aa3b, v23
	v_exp_f32_e32 v210, v210
	v_exp_f32_e32 v211, v211
	v_exp_f32_e32 v212, v212
	v_exp_f32_e32 v213, v213
	v_mul_f32_e32 v4, v4, v180
	v_mul_f32_e32 v5, v5, v181
	v_mul_f32_e32 v6, v6, v182
	v_mul_f32_e32 v7, v7, v183
	v_add_f32_e32 v210, 1.0, v210
	v_add_f32_e32 v211, 1.0, v211
	v_add_f32_e32 v212, 1.0, v212
	v_add_f32_e32 v213, 1.0, v213
	v_rcp_f32_e32 v210, v210
	v_rcp_f32_e32 v211, v211
	v_rcp_f32_e32 v212, v212
	v_rcp_f32_e32 v213, v213
	v_mul_f32_e32 v20, v20, v210
	v_mul_f32_e32 v21, v21, v211
	v_mul_f32_e32 v22, v22, v212
	v_mul_f32_e32 v23, v23, v213
	v_mul_f32_e32 v20, v4, v20
	v_mul_f32_e32 v21, v5, v21
	v_mul_f32_e32 v22, v6, v22
	v_mul_f32_e32 v23, v7, v23
	v_cvt_pk_bf16_f32 v216, v20, v21
	v_cvt_pk_bf16_f32 v217, v22, v23
	ds_write_b64 v195, v[216:217] offset:208
	s_waitcnt lgkmcnt(5)
	v_mul_f32_e32 v24, v24, v184
	v_mul_f32_e32 v25, v25, v185
	v_mul_f32_e32 v26, v26, v186
	v_mul_f32_e32 v27, v27, v187
	v_mul_f32_e32 v210, 0xbfb8aa3b, v24
	v_mul_f32_e32 v211, 0xbfb8aa3b, v25
	v_mul_f32_e32 v212, 0xbfb8aa3b, v26
	v_mul_f32_e32 v213, 0xbfb8aa3b, v27
	v_exp_f32_e32 v210, v210
	v_exp_f32_e32 v211, v211
	v_exp_f32_e32 v212, v212
	v_exp_f32_e32 v213, v213
	v_mul_f32_e32 v8, v8, v184
	v_mul_f32_e32 v9, v9, v185
	v_mul_f32_e32 v10, v10, v186
	v_mul_f32_e32 v11, v11, v187
	v_add_f32_e32 v210, 1.0, v210
	v_add_f32_e32 v211, 1.0, v211
	v_add_f32_e32 v212, 1.0, v212
	v_add_f32_e32 v213, 1.0, v213
	v_rcp_f32_e32 v210, v210
	v_rcp_f32_e32 v211, v211
	v_rcp_f32_e32 v212, v212
	v_rcp_f32_e32 v213, v213
	v_mul_f32_e32 v24, v24, v210
	v_mul_f32_e32 v25, v25, v211
	v_mul_f32_e32 v26, v26, v212
	v_mul_f32_e32 v27, v27, v213
	v_mul_f32_e32 v24, v8, v24
	v_mul_f32_e32 v25, v9, v25
	v_mul_f32_e32 v26, v10, v26
	v_mul_f32_e32 v27, v11, v27
	v_cvt_pk_bf16_f32 v218, v24, v25
	v_cvt_pk_bf16_f32 v219, v26, v27
	ds_write_b64 v195, v[218:219] offset:224
	s_waitcnt lgkmcnt(4)
	v_mul_f32_e32 v28, v28, v188
	v_mul_f32_e32 v29, v29, v189
	v_mul_f32_e32 v30, v30, v190
	v_mul_f32_e32 v31, v31, v191
	v_mul_f32_e32 v210, 0xbfb8aa3b, v28
	v_mul_f32_e32 v211, 0xbfb8aa3b, v29
	v_mul_f32_e32 v212, 0xbfb8aa3b, v30
	v_mul_f32_e32 v213, 0xbfb8aa3b, v31
	v_exp_f32_e32 v210, v210
	v_exp_f32_e32 v211, v211
	v_exp_f32_e32 v212, v212
	v_exp_f32_e32 v213, v213
	v_mul_f32_e32 v12, v12, v188
	v_mul_f32_e32 v13, v13, v189
	v_mul_f32_e32 v14, v14, v190
	v_mul_f32_e32 v15, v15, v191
	v_add_f32_e32 v210, 1.0, v210
	v_add_f32_e32 v211, 1.0, v211
	v_add_f32_e32 v212, 1.0, v212
	v_add_f32_e32 v213, 1.0, v213
	v_rcp_f32_e32 v210, v210
	v_rcp_f32_e32 v211, v211
	v_rcp_f32_e32 v212, v212
	v_rcp_f32_e32 v213, v213
	v_mul_f32_e32 v28, v28, v210
	v_mul_f32_e32 v29, v29, v211
	v_mul_f32_e32 v30, v30, v212
	v_mul_f32_e32 v31, v31, v213
	v_mul_f32_e32 v28, v12, v28
	v_mul_f32_e32 v29, v13, v29
	v_mul_f32_e32 v30, v14, v30
	v_mul_f32_e32 v31, v15, v31
	v_cvt_pk_bf16_f32 v220, v28, v29
	v_cvt_pk_bf16_f32 v221, v30, v31
	ds_write_b64 v195, v[220:221] offset:240
	s_waitcnt lgkmcnt(0)
	ds_read_b64_tr_b16 v[0:1], v196 offset:0
	ds_read_b64_tr_b16 v[2:3], v196 offset:1056
	ds_read_b64_tr_b16 v[4:5], v196 offset:32
	ds_read_b64_tr_b16 v[6:7], v196 offset:1088
	ds_read_b64_tr_b16 v[8:9], v196 offset:64
	ds_read_b64_tr_b16 v[10:11], v196 offset:1120
	ds_read_b64_tr_b16 v[12:13], v196 offset:96
	ds_read_b64_tr_b16 v[14:15], v196 offset:1152
	s_waitcnt lgkmcnt(6)
	ds_read_b64_tr_b16 v[16:17], v196 offset:128
	ds_read_b64_tr_b16 v[18:19], v196 offset:1184
	global_store_dwordx4 v197, v[0:3], s[42:43]
	v_add_u32_e32 v197, 0x16000, v197
	s_waitcnt lgkmcnt(6)
	ds_read_b64_tr_b16 v[20:21], v196 offset:160
	ds_read_b64_tr_b16 v[22:23], v196 offset:1216
	global_store_dwordx4 v197, v[4:7], s[42:43]
	v_add_u32_e32 v197, 0x16000, v197
	s_waitcnt lgkmcnt(6)
	ds_read_b64_tr_b16 v[24:25], v196 offset:192
	ds_read_b64_tr_b16 v[26:27], v196 offset:1248
	global_store_dwordx4 v197, v[8:11], s[42:43]
	v_add_u32_e32 v197, 0x16000, v197
	s_waitcnt lgkmcnt(6)
	ds_read_b64_tr_b16 v[28:29], v196 offset:224
	ds_read_b64_tr_b16 v[30:31], v196 offset:1280
	global_store_dwordx4 v197, v[12:15], s[42:43]
	v_add_u32_e32 v197, 0x16000, v197
	s_waitcnt lgkmcnt(6)
	global_store_dwordx4 v197, v[16:19], s[42:43]
	v_add_u32_e32 v197, 0x16000, v197
	s_waitcnt lgkmcnt(4)
	global_store_dwordx4 v197, v[20:23], s[42:43]
	v_add_u32_e32 v197, 0x16000, v197
	s_waitcnt lgkmcnt(2)
	global_store_dwordx4 v197, v[24:27], s[42:43]
	v_add_u32_e32 v197, 0x16000, v197
	s_waitcnt lgkmcnt(0)
	global_store_dwordx4 v197, v[28:31], s[42:43]
	s_add_i32 s28, s28, s92
	s_cmpk_lt_i32 s28, 0x596
	s_cbranch_scc0 .LBB0_4492
